# EpiGlaProj gate tile: bias vectors loaded once per unit instead of 16 serialized load+store-drain waits
# speedup vs baseline: 1.0069x; 1.0016x over previous
.LBB0_644:
	s_lshr_b32 s2, s8, 1
	v_lshrrev_b32_e32 v172, 1, v172
	v_or_b32_e32 v174, s9, v173
	s_and_b32 s36, s2, 0x60
	v_and_b32_e32 v185, 24, v172
	v_lshlrev_b32_e32 v213, 2, v185
	s_lshl_b32 s98, s36, 2
	s_add_u32 s98, s67, s98
	s_addc_u32 s99, s68, 0
	global_load_dwordx4 v[214:217], v213, s[98:99] offset:16
	global_load_dwordx4 v[218:221], v213, s[98:99]
	s_lshl_b32 s98, s36, 2
	s_add_u32 s98, s69, s98
	s_addc_u32 s99, s88, 0
	global_load_dwordx4 v[222:225], v213, s[98:99] offset:16
	global_load_dwordx4 v[226:229], v213, s[98:99]
	v_readlane_b32 s8, v252, 1
	v_lshlrev_b64 v[190:191], 9, v[174:175]
	v_lshlrev_b64 v[192:193], 11, v[174:175]
	s_andn2_b64 vcc, exec, s[6:7]
	v_or_b32_e32 v196, s36, v185
	v_readlane_b32 s9, v252, 2
	s_cbranch_vccnz .LBB0_656
	s_mov_b64 s[6:7], -1
	s_mov_b64 s[0:1], 0
	s_cmp_lt_i32 s96, 2
	s_mov_b64 s[2:3], 0
	v_cvt_pk_bf16_f32 v152, v152, v153
	v_cvt_pk_bf16_f32 v153, v154, v155
	v_cvt_pk_bf16_f32 v154, v156, v157
	v_cvt_pk_bf16_f32 v155, v158, v159
	s_cbranch_scc1 .LBB0_651
	s_cmp_eq_u32 s96, 2
	s_mov_b64 s[2:3], -1
	s_cbranch_scc0 .LBB0_648
	v_readlane_b32 s2, v251, 63
	v_readlane_b32 s3, v252, 0
	s_nop 1
	v_lshl_add_u64 v[156:157], s[2:3], 0, v[190:191]
	s_mov_b64 s[2:3], 0

.LBB0_656:
	s_nop 1
	v_lshlrev_b64 v[152:153], 10, v[174:175]
	s_and_b64 vcc, exec, s[0:1]
	v_lshl_add_u64 v[186:187], s[8:9], 0, v[152:153]
	v_lshlrev_b32_e32 v172, 2, v196
	s_cbranch_vccz .LBB0_658
	s_lshl_b32 s0, s36, 2
	s_add_u32 s0, s67, s0
	s_addc_u32 s1, s68, 0
	s_waitcnt vmcnt(0)
	v_mov_b64_e32 v[152:153], v[214:215]
	v_mov_b64_e32 v[154:155], v[216:217]
	v_mov_b64_e32 v[156:157], v[218:219]
	v_mov_b64_e32 v[158:159], v[220:221]
	s_mov_b32 s0, 0x7f800000
	s_mov_b32 s2, 0x3d800000
	v_add_f32_e32 v152, v144, v152
	v_add_f32_e32 v156, v148, v156
	v_min_f32_e32 v148, 0, v156
	v_mul_f32_e64 v156, |v156|, s70
	v_exp_f32_e32 v156, v156
	v_min_f32_e32 v144, 0, v152
	v_mul_f32_e64 v152, |v152|, s70
	v_exp_f32_e32 v152, v152
	v_add_f32_e32 v156, 1.0, v156
	v_cmp_gt_f32_e32 vcc, s10, v156
	v_add_f32_e32 v157, v149, v157
	v_add_f32_e32 v152, 1.0, v152
	v_cndmask_b32_e64 v173, 0, 32, vcc
	v_ldexp_f32 v156, v156, v173
	v_log_f32_e32 v156, v156
	v_min_f32_e32 v149, 0, v157
	v_mul_f32_e64 v157, |v157|, s70
	v_exp_f32_e32 v157, v157
	v_mul_f32_e32 v173, 0x3f317217, v156
	v_fma_f32 v173, v156, s77, -v173
	v_fmac_f32_e32 v173, 0x3377d1cf, v156
	v_fmac_f32_e32 v173, 0x3f317217, v156
	v_cmp_lt_f32_e64 s[6:7], |v156|, s0
	v_add_f32_e32 v157, 1.0, v157
	v_add_f32_e32 v153, v145, v153
	v_cndmask_b32_e64 v156, v156, v173, s[6:7]
	v_cndmask_b32_e32 v173, 0, v212, vcc
	v_cmp_gt_f32_e32 vcc, s10, v152
	v_sub_f32_e32 v156, v156, v173
	v_min_f32_e32 v145, 0, v153
	v_cndmask_b32_e64 v173, 0, 32, vcc
	v_ldexp_f32 v152, v152, v173
	v_log_f32_e32 v152, v152
	v_mul_f32_e64 v153, |v153|, s70
	v_exp_f32_e32 v153, v153
	v_add_f32_e32 v158, v150, v158
	v_mul_f32_e32 v173, 0x3f317217, v152
	v_fma_f32 v173, v152, s77, -v173
	v_fmac_f32_e32 v173, 0x3377d1cf, v152
	v_fmac_f32_e32 v173, 0x3f317217, v152
	v_cmp_lt_f32_e64 s[6:7], |v152|, s0
	v_add_f32_e32 v153, 1.0, v153
	v_min_f32_e32 v150, 0, v158
	v_cndmask_b32_e64 v152, v152, v173, s[6:7]
	v_cndmask_b32_e32 v173, 0, v212, vcc
	v_cmp_gt_f32_e32 vcc, s10, v157
	v_sub_f32_e32 v152, v152, v173
	v_mul_f32_e64 v158, |v158|, s70
	v_cndmask_b32_e64 v173, 0, 32, vcc
	v_ldexp_f32 v157, v157, v173
	v_log_f32_e32 v157, v157
	v_exp_f32_e32 v158, v158
	v_add_f32_e32 v154, v146, v154
	v_min_f32_e32 v146, 0, v154
	v_mul_f32_e32 v173, 0x3f317217, v157
	v_fma_f32 v173, v157, s77, -v173
	v_fmac_f32_e32 v173, 0x3377d1cf, v157
	v_fmac_f32_e32 v173, 0x3f317217, v157
	v_cmp_lt_f32_e64 s[6:7], |v157|, s0
	v_add_f32_e32 v158, 1.0, v158
	v_mul_f32_e64 v154, |v154|, s70
	v_cndmask_b32_e64 v157, v157, v173, s[6:7]
	v_cndmask_b32_e32 v173, 0, v212, vcc
	v_cmp_gt_f32_e32 vcc, s10, v153
	v_sub_f32_e32 v157, v157, v173
	v_exp_f32_e32 v154, v154
	v_cndmask_b32_e64 v173, 0, 32, vcc
	v_ldexp_f32 v153, v153, v173
	v_log_f32_e32 v153, v153
	v_add_f32_e32 v154, 1.0, v154
	v_add_f32_e32 v159, v151, v159
	v_min_f32_e32 v151, 0, v159
	v_mul_f32_e32 v173, 0x3f317217, v153
	v_fma_f32 v173, v153, s77, -v173
	v_fmac_f32_e32 v173, 0x3377d1cf, v153
	v_fmac_f32_e32 v173, 0x3f317217, v153
	v_cmp_lt_f32_e64 s[6:7], |v153|, s0
	v_mul_f32_e64 v159, |v159|, s70
	v_exp_f32_e32 v159, v159
	v_cndmask_b32_e64 v153, v153, v173, s[6:7]
	v_cndmask_b32_e32 v173, 0, v212, vcc
	v_cmp_gt_f32_e32 vcc, s10, v158
	v_sub_f32_e32 v153, v153, v173
	v_add_f32_e32 v159, 1.0, v159
	v_cndmask_b32_e64 v173, 0, 32, vcc
	v_ldexp_f32 v158, v158, v173
	v_log_f32_e32 v158, v158
	v_add_f32_e32 v155, v147, v155
	v_min_f32_e32 v147, 0, v155
	v_mul_f32_e64 v155, |v155|, s70
	v_mul_f32_e32 v173, 0x3f317217, v158
	v_fma_f32 v173, v158, s77, -v173
	v_fmac_f32_e32 v173, 0x3377d1cf, v158
	v_fmac_f32_e32 v173, 0x3f317217, v158
	v_cmp_lt_f32_e64 s[6:7], |v158|, s0
	v_exp_f32_e32 v155, v155
	v_pk_add_f32 v[148:149], v[148:149], v[156:157] neg_lo:[0,1] neg_hi:[0,1]
	v_cndmask_b32_e64 v158, v158, v173, s[6:7]
	v_cndmask_b32_e32 v173, 0, v212, vcc
	v_cmp_gt_f32_e32 vcc, s10, v154
	v_sub_f32_e32 v158, v158, v173
	v_add_f32_e32 v155, 1.0, v155
	v_cndmask_b32_e64 v173, 0, 32, vcc
	v_ldexp_f32 v154, v154, v173
	v_log_f32_e32 v154, v154
	v_pk_mul_f32 v[148:149], v[148:149], s[2:3] op_sel_hi:[1,0]
	v_pk_add_f32 v[144:145], v[144:145], v[152:153] neg_lo:[0,1] neg_hi:[0,1]
	v_mul_f32_e32 v173, 0x3f317217, v154
	v_fma_f32 v173, v154, s77, -v173
	v_fmac_f32_e32 v173, 0x3377d1cf, v154
	v_fmac_f32_e32 v173, 0x3f317217, v154
	v_cmp_lt_f32_e64 s[6:7], |v154|, s0
	v_pk_mul_f32 v[144:145], v[144:145], s[2:3] op_sel_hi:[1,0]
	s_nop 0
	v_cndmask_b32_e64 v154, v154, v173, s[6:7]
	v_cndmask_b32_e32 v173, 0, v212, vcc
	v_cmp_gt_f32_e32 vcc, s10, v159
	v_sub_f32_e32 v154, v154, v173
	s_nop 0
	v_cndmask_b32_e64 v173, 0, 32, vcc
	v_ldexp_f32 v159, v159, v173
	v_log_f32_e32 v159, v159
	s_nop 0
	v_mul_f32_e32 v173, 0x3f317217, v159
	v_fma_f32 v173, v159, s77, -v173
	v_fmac_f32_e32 v173, 0x3377d1cf, v159
	v_fmac_f32_e32 v173, 0x3f317217, v159
	v_cmp_lt_f32_e64 s[6:7], |v159|, s0
	s_nop 1
	v_cndmask_b32_e64 v159, v159, v173, s[6:7]
	v_cndmask_b32_e32 v173, 0, v212, vcc
	v_cmp_gt_f32_e32 vcc, s10, v155
	v_sub_f32_e32 v159, v159, v173
	v_pk_add_f32 v[150:151], v[150:151], v[158:159] neg_lo:[0,1] neg_hi:[0,1]
	v_cndmask_b32_e64 v156, 0, 32, vcc
	v_ldexp_f32 v155, v155, v156
	v_log_f32_e32 v155, v155
	v_mov_b32_e32 v173, v177
	v_pk_mul_f32 v[150:151], v[150:151], s[2:3] op_sel_hi:[1,0]
	v_lshl_add_u64 v[152:153], v[186:187], 0, v[172:173]
	v_mul_f32_e32 v156, 0x3f317217, v155
	v_fma_f32 v156, v155, s77, -v156
	v_fmac_f32_e32 v156, 0x3377d1cf, v155
	v_fmac_f32_e32 v156, 0x3f317217, v155
	v_cmp_lt_f32_e64 s[6:7], |v155|, s0
	s_nop 1
	v_cndmask_b32_e64 v155, v155, v156, s[6:7]
	v_cndmask_b32_e32 v156, 0, v212, vcc
	v_sub_f32_e32 v155, v155, v156
	v_pk_add_f32 v[146:147], v[146:147], v[154:155] neg_lo:[0,1] neg_hi:[0,1]
	s_nop 0
	v_pk_mul_f32 v[146:147], v[146:147], s[2:3] op_sel_hi:[1,0]
	global_store_dwordx4 v[152:153], v[148:151], off
	global_store_dwordx4 v[152:153], v[144:147], off offset:16

.LBB0_671:
	s_and_b64 vcc, exec, s[0:1]
	s_cbranch_vccz .LBB0_673
	s_lshl_b32 s0, s36, 2
	s_add_u32 s0, s69, s0
	s_addc_u32 s1, s88, 0
	v_mov_b64_e32 v[144:145], v[222:223]
	v_mov_b64_e32 v[146:147], v[224:225]
	v_mov_b64_e32 v[148:149], v[226:227]
	v_mov_b64_e32 v[150:151], v[228:229]
	s_mov_b32 s0, 0x7f800000
	s_mov_b32 s2, 0x3d800000
	v_mov_b32_e32 v173, v177
	v_add_f32_e32 v144, v136, v144
	v_add_f32_e32 v148, v140, v148
	v_min_f32_e32 v140, 0, v148
	v_mul_f32_e64 v148, |v148|, s70
	v_exp_f32_e32 v148, v148
	v_min_f32_e32 v136, 0, v144
	v_mul_f32_e64 v144, |v144|, s70
	v_exp_f32_e32 v144, v144
	v_add_f32_e32 v148, 1.0, v148
	v_cmp_gt_f32_e32 vcc, s10, v148
	v_add_f32_e32 v149, v141, v149
	v_add_f32_e32 v144, 1.0, v144
	v_cndmask_b32_e64 v152, 0, 32, vcc
	v_ldexp_f32 v148, v148, v152
	v_log_f32_e32 v148, v148
	v_min_f32_e32 v141, 0, v149
	v_mul_f32_e64 v149, |v149|, s70
	v_exp_f32_e32 v149, v149
	v_mul_f32_e32 v152, 0x3f317217, v148
	v_fma_f32 v152, v148, s77, -v152
	v_fmac_f32_e32 v152, 0x3377d1cf, v148
	v_fmac_f32_e32 v152, 0x3f317217, v148
	v_cmp_lt_f32_e64 s[6:7], |v148|, s0
	v_add_f32_e32 v149, 1.0, v149
	v_add_f32_e32 v145, v137, v145
	v_cndmask_b32_e64 v148, v148, v152, s[6:7]
	v_cndmask_b32_e32 v152, 0, v212, vcc
	v_cmp_gt_f32_e32 vcc, s10, v144
	v_sub_f32_e32 v148, v148, v152
	v_min_f32_e32 v137, 0, v145
	v_cndmask_b32_e64 v152, 0, 32, vcc
	v_ldexp_f32 v144, v144, v152
	v_log_f32_e32 v144, v144
	v_mul_f32_e64 v145, |v145|, s70
	v_exp_f32_e32 v145, v145
	v_add_f32_e32 v150, v142, v150
	v_mul_f32_e32 v152, 0x3f317217, v144
	v_fma_f32 v152, v144, s77, -v152
	v_fmac_f32_e32 v152, 0x3377d1cf, v144
	v_fmac_f32_e32 v152, 0x3f317217, v144
	v_cmp_lt_f32_e64 s[6:7], |v144|, s0
	v_add_f32_e32 v145, 1.0, v145
	v_min_f32_e32 v142, 0, v150
	v_cndmask_b32_e64 v144, v144, v152, s[6:7]
	v_cndmask_b32_e32 v152, 0, v212, vcc
	v_cmp_gt_f32_e32 vcc, s10, v149
	v_sub_f32_e32 v144, v144, v152
	v_mul_f32_e64 v150, |v150|, s70
	v_cndmask_b32_e64 v152, 0, 32, vcc
	v_ldexp_f32 v149, v149, v152
	v_log_f32_e32 v149, v149
	v_exp_f32_e32 v150, v150
	v_add_f32_e32 v146, v138, v146
	v_min_f32_e32 v138, 0, v146
	v_mul_f32_e32 v152, 0x3f317217, v149
	v_fma_f32 v152, v149, s77, -v152
	v_fmac_f32_e32 v152, 0x3377d1cf, v149
	v_fmac_f32_e32 v152, 0x3f317217, v149
	v_cmp_lt_f32_e64 s[6:7], |v149|, s0
	v_add_f32_e32 v150, 1.0, v150
	v_mul_f32_e64 v146, |v146|, s70
	v_cndmask_b32_e64 v149, v149, v152, s[6:7]
	v_cndmask_b32_e32 v152, 0, v212, vcc
	v_cmp_gt_f32_e32 vcc, s10, v145
	v_sub_f32_e32 v149, v149, v152
	v_exp_f32_e32 v146, v146
	v_cndmask_b32_e64 v152, 0, 32, vcc
	v_ldexp_f32 v145, v145, v152
	v_log_f32_e32 v145, v145
	v_add_f32_e32 v146, 1.0, v146
	v_add_f32_e32 v151, v143, v151
	v_min_f32_e32 v143, 0, v151
	v_mul_f32_e32 v152, 0x3f317217, v145
	v_fma_f32 v152, v145, s77, -v152
	v_fmac_f32_e32 v152, 0x3377d1cf, v145
	v_fmac_f32_e32 v152, 0x3f317217, v145
	v_cmp_lt_f32_e64 s[6:7], |v145|, s0
	v_mul_f32_e64 v151, |v151|, s70
	v_exp_f32_e32 v151, v151
	v_cndmask_b32_e64 v145, v145, v152, s[6:7]
	v_cndmask_b32_e32 v152, 0, v212, vcc
	v_cmp_gt_f32_e32 vcc, s10, v150
	v_sub_f32_e32 v145, v145, v152
	v_add_f32_e32 v151, 1.0, v151
	v_cndmask_b32_e64 v152, 0, 32, vcc
	v_ldexp_f32 v150, v150, v152
	v_log_f32_e32 v150, v150
	v_add_f32_e32 v147, v139, v147
	v_min_f32_e32 v139, 0, v147
	v_mul_f32_e64 v147, |v147|, s70
	v_mul_f32_e32 v152, 0x3f317217, v150
	v_fma_f32 v152, v150, s77, -v152
	v_fmac_f32_e32 v152, 0x3377d1cf, v150
	v_fmac_f32_e32 v152, 0x3f317217, v150
	v_cmp_lt_f32_e64 s[6:7], |v150|, s0
	v_exp_f32_e32 v147, v147
	v_pk_add_f32 v[140:141], v[140:141], v[148:149] neg_lo:[0,1] neg_hi:[0,1]
	v_cndmask_b32_e64 v150, v150, v152, s[6:7]
	v_cndmask_b32_e32 v152, 0, v212, vcc
	v_cmp_gt_f32_e32 vcc, s10, v146
	v_sub_f32_e32 v150, v150, v152
	v_add_f32_e32 v147, 1.0, v147
	v_cndmask_b32_e64 v152, 0, 32, vcc
	v_ldexp_f32 v146, v146, v152
	v_log_f32_e32 v146, v146
	v_pk_mul_f32 v[140:141], v[140:141], s[2:3] op_sel_hi:[1,0]
	v_pk_add_f32 v[136:137], v[136:137], v[144:145] neg_lo:[0,1] neg_hi:[0,1]
	v_lshl_add_u64 v[144:145], v[186:187], 0, v[172:173]
	v_mul_f32_e32 v152, 0x3f317217, v146
	v_fma_f32 v152, v146, s77, -v152
	v_fmac_f32_e32 v152, 0x3377d1cf, v146
	v_fmac_f32_e32 v152, 0x3f317217, v146
	v_cmp_lt_f32_e64 s[6:7], |v146|, s0
	v_pk_mul_f32 v[136:137], v[136:137], s[2:3] op_sel_hi:[1,0]
	s_nop 0
	v_cndmask_b32_e64 v146, v146, v152, s[6:7]
	v_cndmask_b32_e32 v152, 0, v212, vcc
	v_cmp_gt_f32_e32 vcc, s10, v151
	v_sub_f32_e32 v146, v146, v152
	s_nop 0
	v_cndmask_b32_e64 v152, 0, 32, vcc
	v_ldexp_f32 v151, v151, v152
	v_log_f32_e32 v151, v151
	s_nop 0
	v_mul_f32_e32 v152, 0x3f317217, v151
	v_fma_f32 v152, v151, s77, -v152
	v_fmac_f32_e32 v152, 0x3377d1cf, v151
	v_fmac_f32_e32 v152, 0x3f317217, v151
	v_cmp_lt_f32_e64 s[6:7], |v151|, s0
	s_nop 1
	v_cndmask_b32_e64 v151, v151, v152, s[6:7]
	v_cndmask_b32_e32 v152, 0, v212, vcc
	v_cmp_gt_f32_e32 vcc, s10, v147
	v_sub_f32_e32 v151, v151, v152
	v_pk_add_f32 v[142:143], v[142:143], v[150:151] neg_lo:[0,1] neg_hi:[0,1]
	v_cndmask_b32_e64 v148, 0, 32, vcc
	v_ldexp_f32 v147, v147, v148
	v_log_f32_e32 v147, v147
	v_pk_mul_f32 v[142:143], v[142:143], s[2:3] op_sel_hi:[1,0]
	v_mul_f32_e32 v148, 0x3f317217, v147
	v_fma_f32 v148, v147, s77, -v148
	v_fmac_f32_e32 v148, 0x3377d1cf, v147
	v_fmac_f32_e32 v148, 0x3f317217, v147
	v_cmp_lt_f32_e64 s[6:7], |v147|, s0
	s_nop 1
	v_cndmask_b32_e64 v147, v147, v148, s[6:7]
	v_cndmask_b32_e32 v148, 0, v212, vcc
	v_sub_f32_e32 v147, v147, v148
	v_pk_add_f32 v[138:139], v[138:139], v[146:147] neg_lo:[0,1] neg_hi:[0,1]
	s_nop 0
	v_pk_mul_f32 v[138:139], v[138:139], s[2:3] op_sel_hi:[1,0]
	global_store_dwordx4 v[144:145], v[140:143], off offset:512
	global_store_dwordx4 v[144:145], v[136:139], off offset:528

.LBB0_696:
	s_nop 1
	v_lshlrev_b64 v[136:137], 10, v[144:145]
	s_and_b64 vcc, exec, s[0:1]
	v_lshl_add_u64 v[144:145], s[8:9], 0, v[136:137]
	s_cbranch_vccz .LBB0_698
	s_lshl_b32 s0, s36, 2
	s_add_u32 s0, s67, s0
	s_addc_u32 s1, s68, 0
	v_mov_b64_e32 v[136:137], v[214:215]
	v_mov_b64_e32 v[138:139], v[216:217]
	v_mov_b64_e32 v[140:141], v[218:219]
	v_mov_b64_e32 v[142:143], v[220:221]
	s_mov_b32 s0, 0x7f800000
	s_mov_b32 s2, 0x3d800000
	v_mov_b32_e32 v173, v177
	v_add_f32_e32 v136, v128, v136
	v_add_f32_e32 v140, v132, v140
	v_min_f32_e32 v132, 0, v140
	v_mul_f32_e64 v140, |v140|, s70
	v_exp_f32_e32 v140, v140
	v_min_f32_e32 v128, 0, v136
	v_mul_f32_e64 v136, |v136|, s70
	v_exp_f32_e32 v136, v136
	v_add_f32_e32 v140, 1.0, v140
	v_cmp_gt_f32_e32 vcc, s10, v140
	v_add_f32_e32 v141, v133, v141
	v_add_f32_e32 v136, 1.0, v136
	v_cndmask_b32_e64 v151, 0, 32, vcc
	v_ldexp_f32 v140, v140, v151
	v_log_f32_e32 v140, v140
	v_min_f32_e32 v133, 0, v141
	v_mul_f32_e64 v141, |v141|, s70
	v_exp_f32_e32 v141, v141
	v_mul_f32_e32 v151, 0x3f317217, v140
	v_fma_f32 v151, v140, s77, -v151
	v_fmac_f32_e32 v151, 0x3377d1cf, v140
	v_fmac_f32_e32 v151, 0x3f317217, v140
	v_cmp_lt_f32_e64 s[4:5], |v140|, s0
	v_add_f32_e32 v141, 1.0, v141
	v_add_f32_e32 v137, v129, v137
	v_cndmask_b32_e64 v140, v140, v151, s[4:5]
	v_cndmask_b32_e32 v151, 0, v212, vcc
	v_cmp_gt_f32_e32 vcc, s10, v136
	v_sub_f32_e32 v140, v140, v151
	v_min_f32_e32 v129, 0, v137
	v_cndmask_b32_e64 v151, 0, 32, vcc
	v_ldexp_f32 v136, v136, v151
	v_log_f32_e32 v136, v136
	v_mul_f32_e64 v137, |v137|, s70
	v_exp_f32_e32 v137, v137
	v_add_f32_e32 v142, v134, v142
	v_mul_f32_e32 v151, 0x3f317217, v136
	v_fma_f32 v151, v136, s77, -v151
	v_fmac_f32_e32 v151, 0x3377d1cf, v136
	v_fmac_f32_e32 v151, 0x3f317217, v136
	v_cmp_lt_f32_e64 s[4:5], |v136|, s0
	v_add_f32_e32 v137, 1.0, v137
	v_min_f32_e32 v134, 0, v142
	v_cndmask_b32_e64 v136, v136, v151, s[4:5]
	v_cndmask_b32_e32 v151, 0, v212, vcc
	v_cmp_gt_f32_e32 vcc, s10, v141
	v_sub_f32_e32 v136, v136, v151
	v_mul_f32_e64 v142, |v142|, s70
	v_cndmask_b32_e64 v151, 0, 32, vcc
	v_ldexp_f32 v141, v141, v151
	v_log_f32_e32 v141, v141
	v_exp_f32_e32 v142, v142
	v_add_f32_e32 v138, v130, v138
	v_min_f32_e32 v130, 0, v138
	v_mul_f32_e32 v151, 0x3f317217, v141
	v_fma_f32 v151, v141, s77, -v151
	v_fmac_f32_e32 v151, 0x3377d1cf, v141
	v_fmac_f32_e32 v151, 0x3f317217, v141
	v_cmp_lt_f32_e64 s[4:5], |v141|, s0
	v_add_f32_e32 v142, 1.0, v142
	v_mul_f32_e64 v138, |v138|, s70
	v_cndmask_b32_e64 v141, v141, v151, s[4:5]
	v_cndmask_b32_e32 v151, 0, v212, vcc
	v_cmp_gt_f32_e32 vcc, s10, v137
	v_sub_f32_e32 v141, v141, v151
	v_exp_f32_e32 v138, v138
	v_cndmask_b32_e64 v151, 0, 32, vcc
	v_ldexp_f32 v137, v137, v151
	v_log_f32_e32 v137, v137
	v_add_f32_e32 v138, 1.0, v138
	v_add_f32_e32 v143, v135, v143
	v_min_f32_e32 v135, 0, v143
	v_mul_f32_e32 v151, 0x3f317217, v137
	v_fma_f32 v151, v137, s77, -v151
	v_fmac_f32_e32 v151, 0x3377d1cf, v137
	v_fmac_f32_e32 v151, 0x3f317217, v137
	v_cmp_lt_f32_e64 s[4:5], |v137|, s0
	v_mul_f32_e64 v143, |v143|, s70
	v_exp_f32_e32 v143, v143
	v_cndmask_b32_e64 v137, v137, v151, s[4:5]
	v_cndmask_b32_e32 v151, 0, v212, vcc
	v_cmp_gt_f32_e32 vcc, s10, v142
	v_sub_f32_e32 v137, v137, v151
	v_add_f32_e32 v143, 1.0, v143
	v_cndmask_b32_e64 v151, 0, 32, vcc
	v_ldexp_f32 v142, v142, v151
	v_log_f32_e32 v142, v142
	v_add_f32_e32 v139, v131, v139
	v_min_f32_e32 v131, 0, v139
	v_mul_f32_e64 v139, |v139|, s70
	v_mul_f32_e32 v151, 0x3f317217, v142
	v_fma_f32 v151, v142, s77, -v151
	v_fmac_f32_e32 v151, 0x3377d1cf, v142
	v_fmac_f32_e32 v151, 0x3f317217, v142
	v_cmp_lt_f32_e64 s[4:5], |v142|, s0
	v_exp_f32_e32 v139, v139
	v_pk_add_f32 v[132:133], v[132:133], v[140:141] neg_lo:[0,1] neg_hi:[0,1]
	v_cndmask_b32_e64 v142, v142, v151, s[4:5]
	v_cndmask_b32_e32 v151, 0, v212, vcc
	v_cmp_gt_f32_e32 vcc, s10, v138
	v_sub_f32_e32 v142, v142, v151
	v_add_f32_e32 v139, 1.0, v139
	v_cndmask_b32_e64 v151, 0, 32, vcc
	v_ldexp_f32 v138, v138, v151
	v_log_f32_e32 v138, v138
	v_pk_mul_f32 v[132:133], v[132:133], s[2:3] op_sel_hi:[1,0]
	v_pk_add_f32 v[128:129], v[128:129], v[136:137] neg_lo:[0,1] neg_hi:[0,1]
	v_lshl_add_u64 v[136:137], v[144:145], 0, v[172:173]
	v_mul_f32_e32 v151, 0x3f317217, v138
	v_fma_f32 v151, v138, s77, -v151
	v_fmac_f32_e32 v151, 0x3377d1cf, v138
	v_fmac_f32_e32 v151, 0x3f317217, v138
	v_cmp_lt_f32_e64 s[4:5], |v138|, s0
	v_pk_mul_f32 v[128:129], v[128:129], s[2:3] op_sel_hi:[1,0]
	s_nop 0
	v_cndmask_b32_e64 v138, v138, v151, s[4:5]
	v_cndmask_b32_e32 v151, 0, v212, vcc
	v_cmp_gt_f32_e32 vcc, s10, v143
	v_sub_f32_e32 v138, v138, v151
	s_nop 0
	v_cndmask_b32_e64 v151, 0, 32, vcc
	v_ldexp_f32 v143, v143, v151
	v_log_f32_e32 v143, v143
	s_nop 0
	v_mul_f32_e32 v151, 0x3f317217, v143
	v_fma_f32 v151, v143, s77, -v151
	v_fmac_f32_e32 v151, 0x3377d1cf, v143
	v_fmac_f32_e32 v151, 0x3f317217, v143
	v_cmp_lt_f32_e64 s[4:5], |v143|, s0
	s_nop 1
	v_cndmask_b32_e64 v143, v143, v151, s[4:5]
	v_cndmask_b32_e32 v151, 0, v212, vcc
	v_cmp_gt_f32_e32 vcc, s10, v139
	v_sub_f32_e32 v143, v143, v151
	v_pk_add_f32 v[134:135], v[134:135], v[142:143] neg_lo:[0,1] neg_hi:[0,1]
	v_cndmask_b32_e64 v140, 0, 32, vcc
	v_ldexp_f32 v139, v139, v140
	v_log_f32_e32 v139, v139
	v_pk_mul_f32 v[134:135], v[134:135], s[2:3] op_sel_hi:[1,0]
	v_mul_f32_e32 v140, 0x3f317217, v139
	v_fma_f32 v140, v139, s77, -v140
	v_fmac_f32_e32 v140, 0x3377d1cf, v139
	v_fmac_f32_e32 v140, 0x3f317217, v139
	v_cmp_lt_f32_e64 s[4:5], |v139|, s0
	s_nop 1
	v_cndmask_b32_e64 v139, v139, v140, s[4:5]
	v_cndmask_b32_e32 v140, 0, v212, vcc
	v_sub_f32_e32 v139, v139, v140
	v_pk_add_f32 v[130:131], v[130:131], v[138:139] neg_lo:[0,1] neg_hi:[0,1]
	s_nop 0
	v_pk_mul_f32 v[130:131], v[130:131], s[2:3] op_sel_hi:[1,0]
	global_store_dwordx4 v[136:137], v[132:135], off
	global_store_dwordx4 v[136:137], v[128:131], off offset:16

.LBB0_711:
	s_and_b64 vcc, exec, s[0:1]
	s_cbranch_vccz .LBB0_713
	s_lshl_b32 s0, s36, 2
	s_add_u32 s0, s69, s0
	s_addc_u32 s1, s88, 0
	v_mov_b64_e32 v[128:129], v[222:223]
	v_mov_b64_e32 v[130:131], v[224:225]
	v_mov_b64_e32 v[132:133], v[226:227]
	v_mov_b64_e32 v[134:135], v[228:229]
	s_mov_b32 s0, 0x7f800000
	s_mov_b32 s2, 0x3d800000
	v_mov_b32_e32 v173, v177
	v_add_f32_e32 v128, v120, v128
	v_add_f32_e32 v132, v124, v132
	v_min_f32_e32 v124, 0, v132
	v_mul_f32_e64 v132, |v132|, s70
	v_exp_f32_e32 v132, v132
	v_min_f32_e32 v120, 0, v128
	v_mul_f32_e64 v128, |v128|, s70
	v_exp_f32_e32 v128, v128
	v_add_f32_e32 v132, 1.0, v132
	v_cmp_gt_f32_e32 vcc, s10, v132
	v_add_f32_e32 v133, v125, v133
	v_add_f32_e32 v128, 1.0, v128
	v_cndmask_b32_e64 v136, 0, 32, vcc
	v_ldexp_f32 v132, v132, v136
	v_log_f32_e32 v132, v132
	v_min_f32_e32 v125, 0, v133
	v_mul_f32_e64 v133, |v133|, s70
	v_exp_f32_e32 v133, v133
	v_mul_f32_e32 v136, 0x3f317217, v132
	v_fma_f32 v136, v132, s77, -v136
	v_fmac_f32_e32 v136, 0x3377d1cf, v132
	v_fmac_f32_e32 v136, 0x3f317217, v132
	v_cmp_lt_f32_e64 s[4:5], |v132|, s0
	v_add_f32_e32 v133, 1.0, v133
	v_add_f32_e32 v129, v121, v129
	v_cndmask_b32_e64 v132, v132, v136, s[4:5]
	v_cndmask_b32_e32 v136, 0, v212, vcc
	v_cmp_gt_f32_e32 vcc, s10, v128
	v_sub_f32_e32 v132, v132, v136
	v_min_f32_e32 v121, 0, v129
	v_cndmask_b32_e64 v136, 0, 32, vcc
	v_ldexp_f32 v128, v128, v136
	v_log_f32_e32 v128, v128
	v_mul_f32_e64 v129, |v129|, s70
	v_exp_f32_e32 v129, v129
	v_add_f32_e32 v134, v126, v134
	v_mul_f32_e32 v136, 0x3f317217, v128
	v_fma_f32 v136, v128, s77, -v136
	v_fmac_f32_e32 v136, 0x3377d1cf, v128
	v_fmac_f32_e32 v136, 0x3f317217, v128
	v_cmp_lt_f32_e64 s[4:5], |v128|, s0
	v_add_f32_e32 v129, 1.0, v129
	v_min_f32_e32 v126, 0, v134
	v_cndmask_b32_e64 v128, v128, v136, s[4:5]
	v_cndmask_b32_e32 v136, 0, v212, vcc
	v_cmp_gt_f32_e32 vcc, s10, v133
	v_sub_f32_e32 v128, v128, v136
	v_mul_f32_e64 v134, |v134|, s70
	v_cndmask_b32_e64 v136, 0, 32, vcc
	v_ldexp_f32 v133, v133, v136
	v_log_f32_e32 v133, v133
	v_exp_f32_e32 v134, v134
	v_add_f32_e32 v130, v122, v130
	v_min_f32_e32 v122, 0, v130
	v_mul_f32_e32 v136, 0x3f317217, v133
	v_fma_f32 v136, v133, s77, -v136
	v_fmac_f32_e32 v136, 0x3377d1cf, v133
	v_fmac_f32_e32 v136, 0x3f317217, v133
	v_cmp_lt_f32_e64 s[4:5], |v133|, s0
	v_add_f32_e32 v134, 1.0, v134
	v_mul_f32_e64 v130, |v130|, s70
	v_cndmask_b32_e64 v133, v133, v136, s[4:5]
	v_cndmask_b32_e32 v136, 0, v212, vcc
	v_cmp_gt_f32_e32 vcc, s10, v129
	v_sub_f32_e32 v133, v133, v136
	v_exp_f32_e32 v130, v130
	v_cndmask_b32_e64 v136, 0, 32, vcc
	v_ldexp_f32 v129, v129, v136
	v_log_f32_e32 v129, v129
	v_add_f32_e32 v130, 1.0, v130
	v_add_f32_e32 v135, v127, v135
	v_min_f32_e32 v127, 0, v135
	v_mul_f32_e32 v136, 0x3f317217, v129
	v_fma_f32 v136, v129, s77, -v136
	v_fmac_f32_e32 v136, 0x3377d1cf, v129
	v_fmac_f32_e32 v136, 0x3f317217, v129
	v_cmp_lt_f32_e64 s[4:5], |v129|, s0
	v_mul_f32_e64 v135, |v135|, s70
	v_exp_f32_e32 v135, v135
	v_cndmask_b32_e64 v129, v129, v136, s[4:5]
	v_cndmask_b32_e32 v136, 0, v212, vcc
	v_cmp_gt_f32_e32 vcc, s10, v134
	v_sub_f32_e32 v129, v129, v136
	v_add_f32_e32 v135, 1.0, v135
	v_cndmask_b32_e64 v136, 0, 32, vcc
	v_ldexp_f32 v134, v134, v136
	v_log_f32_e32 v134, v134
	v_add_f32_e32 v131, v123, v131
	v_min_f32_e32 v123, 0, v131
	v_mul_f32_e64 v131, |v131|, s70
	v_mul_f32_e32 v136, 0x3f317217, v134
	v_fma_f32 v136, v134, s77, -v136
	v_fmac_f32_e32 v136, 0x3377d1cf, v134
	v_fmac_f32_e32 v136, 0x3f317217, v134
	v_cmp_lt_f32_e64 s[4:5], |v134|, s0
	v_exp_f32_e32 v131, v131
	v_pk_add_f32 v[124:125], v[124:125], v[132:133] neg_lo:[0,1] neg_hi:[0,1]
	v_cndmask_b32_e64 v134, v134, v136, s[4:5]
	v_cndmask_b32_e32 v136, 0, v212, vcc
	v_cmp_gt_f32_e32 vcc, s10, v130
	v_sub_f32_e32 v134, v134, v136
	v_add_f32_e32 v131, 1.0, v131
	v_cndmask_b32_e64 v136, 0, 32, vcc
	v_ldexp_f32 v130, v130, v136
	v_log_f32_e32 v130, v130
	v_pk_mul_f32 v[124:125], v[124:125], s[2:3] op_sel_hi:[1,0]
	v_pk_add_f32 v[120:121], v[120:121], v[128:129] neg_lo:[0,1] neg_hi:[0,1]
	v_lshl_add_u64 v[128:129], v[144:145], 0, v[172:173]
	v_mul_f32_e32 v136, 0x3f317217, v130
	v_fma_f32 v136, v130, s77, -v136
	v_fmac_f32_e32 v136, 0x3377d1cf, v130
	v_fmac_f32_e32 v136, 0x3f317217, v130
	v_cmp_lt_f32_e64 s[4:5], |v130|, s0
	v_pk_mul_f32 v[120:121], v[120:121], s[2:3] op_sel_hi:[1,0]
	s_nop 0
	v_cndmask_b32_e64 v130, v130, v136, s[4:5]
	v_cndmask_b32_e32 v136, 0, v212, vcc
	v_cmp_gt_f32_e32 vcc, s10, v135
	v_sub_f32_e32 v130, v130, v136
	s_nop 0
	v_cndmask_b32_e64 v136, 0, 32, vcc
	v_ldexp_f32 v135, v135, v136
	v_log_f32_e32 v135, v135
	s_nop 0
	v_mul_f32_e32 v136, 0x3f317217, v135
	v_fma_f32 v136, v135, s77, -v136
	v_fmac_f32_e32 v136, 0x3377d1cf, v135
	v_fmac_f32_e32 v136, 0x3f317217, v135
	v_cmp_lt_f32_e64 s[4:5], |v135|, s0
	s_nop 1
	v_cndmask_b32_e64 v135, v135, v136, s[4:5]
	v_cndmask_b32_e32 v136, 0, v212, vcc
	v_cmp_gt_f32_e32 vcc, s10, v131
	v_sub_f32_e32 v135, v135, v136
	v_pk_add_f32 v[126:127], v[126:127], v[134:135] neg_lo:[0,1] neg_hi:[0,1]
	v_cndmask_b32_e64 v132, 0, 32, vcc
	v_ldexp_f32 v131, v131, v132
	v_log_f32_e32 v131, v131
	v_pk_mul_f32 v[126:127], v[126:127], s[2:3] op_sel_hi:[1,0]
	v_mul_f32_e32 v132, 0x3f317217, v131
	v_fma_f32 v132, v131, s77, -v132
	v_fmac_f32_e32 v132, 0x3377d1cf, v131
	v_fmac_f32_e32 v132, 0x3f317217, v131
	v_cmp_lt_f32_e64 s[4:5], |v131|, s0
	s_nop 1
	v_cndmask_b32_e64 v131, v131, v132, s[4:5]
	v_cndmask_b32_e32 v132, 0, v212, vcc
	v_sub_f32_e32 v131, v131, v132
	v_pk_add_f32 v[122:123], v[122:123], v[130:131] neg_lo:[0,1] neg_hi:[0,1]
	s_nop 0
	v_pk_mul_f32 v[122:123], v[122:123], s[2:3] op_sel_hi:[1,0]
	global_store_dwordx4 v[128:129], v[124:127], off offset:512
	global_store_dwordx4 v[128:129], v[120:123], off offset:528

.LBB0_736:
	s_nop 1
	v_lshlrev_b64 v[112:113], 10, v[122:123]
	s_and_b64 vcc, exec, s[0:1]
	v_lshl_add_u64 v[122:123], s[8:9], 0, v[112:113]
	s_cbranch_vccz .LBB0_738
	s_lshl_b32 s0, s36, 2
	s_add_u32 s0, s67, s0
	s_addc_u32 s1, s68, 0
	v_mov_b64_e32 v[112:113], v[214:215]
	v_mov_b64_e32 v[114:115], v[216:217]
	v_mov_b64_e32 v[116:117], v[218:219]
	v_mov_b64_e32 v[118:119], v[220:221]
	s_mov_b32 s0, 0x7f800000
	s_mov_b32 s2, 0x3d800000
	v_mov_b32_e32 v173, v177
	v_add_f32_e32 v112, v104, v112
	v_add_f32_e32 v116, v108, v116
	v_min_f32_e32 v108, 0, v116
	v_mul_f32_e64 v116, |v116|, s70
	v_exp_f32_e32 v116, v116
	v_min_f32_e32 v104, 0, v112
	v_mul_f32_e64 v112, |v112|, s70
	v_exp_f32_e32 v112, v112
	v_add_f32_e32 v116, 1.0, v116
	v_cmp_gt_f32_e32 vcc, s10, v116
	v_add_f32_e32 v117, v109, v117
	v_add_f32_e32 v112, 1.0, v112
	v_cndmask_b32_e64 v121, 0, 32, vcc
	v_ldexp_f32 v116, v116, v121
	v_log_f32_e32 v116, v116
	v_min_f32_e32 v109, 0, v117
	v_mul_f32_e64 v117, |v117|, s70
	v_exp_f32_e32 v117, v117
	v_mul_f32_e32 v121, 0x3f317217, v116
	v_fma_f32 v121, v116, s77, -v121
	v_fmac_f32_e32 v121, 0x3377d1cf, v116
	v_fmac_f32_e32 v121, 0x3f317217, v116
	v_cmp_lt_f32_e64 s[6:7], |v116|, s0
	v_add_f32_e32 v117, 1.0, v117
	v_add_f32_e32 v113, v105, v113
	v_cndmask_b32_e64 v116, v116, v121, s[6:7]
	v_cndmask_b32_e32 v121, 0, v212, vcc
	v_cmp_gt_f32_e32 vcc, s10, v112
	v_sub_f32_e32 v116, v116, v121
	v_min_f32_e32 v105, 0, v113
	v_cndmask_b32_e64 v121, 0, 32, vcc
	v_ldexp_f32 v112, v112, v121
	v_log_f32_e32 v112, v112
	v_mul_f32_e64 v113, |v113|, s70
	v_exp_f32_e32 v113, v113
	v_add_f32_e32 v118, v110, v118
	v_mul_f32_e32 v121, 0x3f317217, v112
	v_fma_f32 v121, v112, s77, -v121
	v_fmac_f32_e32 v121, 0x3377d1cf, v112
	v_fmac_f32_e32 v121, 0x3f317217, v112
	v_cmp_lt_f32_e64 s[6:7], |v112|, s0
	v_add_f32_e32 v113, 1.0, v113
	v_min_f32_e32 v110, 0, v118
	v_cndmask_b32_e64 v112, v112, v121, s[6:7]
	v_cndmask_b32_e32 v121, 0, v212, vcc
	v_cmp_gt_f32_e32 vcc, s10, v117
	v_sub_f32_e32 v112, v112, v121
	v_mul_f32_e64 v118, |v118|, s70
	v_cndmask_b32_e64 v121, 0, 32, vcc
	v_ldexp_f32 v117, v117, v121
	v_log_f32_e32 v117, v117
	v_exp_f32_e32 v118, v118
	v_add_f32_e32 v114, v106, v114
	v_min_f32_e32 v106, 0, v114
	v_mul_f32_e32 v121, 0x3f317217, v117
	v_fma_f32 v121, v117, s77, -v121
	v_fmac_f32_e32 v121, 0x3377d1cf, v117
	v_fmac_f32_e32 v121, 0x3f317217, v117
	v_cmp_lt_f32_e64 s[6:7], |v117|, s0
	v_add_f32_e32 v118, 1.0, v118
	v_mul_f32_e64 v114, |v114|, s70
	v_cndmask_b32_e64 v117, v117, v121, s[6:7]
	v_cndmask_b32_e32 v121, 0, v212, vcc
	v_cmp_gt_f32_e32 vcc, s10, v113
	v_sub_f32_e32 v117, v117, v121
	v_exp_f32_e32 v114, v114
	v_cndmask_b32_e64 v121, 0, 32, vcc
	v_ldexp_f32 v113, v113, v121
	v_log_f32_e32 v113, v113
	v_add_f32_e32 v114, 1.0, v114
	v_add_f32_e32 v119, v111, v119
	v_min_f32_e32 v111, 0, v119
	v_mul_f32_e32 v121, 0x3f317217, v113
	v_fma_f32 v121, v113, s77, -v121
	v_fmac_f32_e32 v121, 0x3377d1cf, v113
	v_fmac_f32_e32 v121, 0x3f317217, v113
	v_cmp_lt_f32_e64 s[6:7], |v113|, s0
	v_mul_f32_e64 v119, |v119|, s70
	v_exp_f32_e32 v119, v119
	v_cndmask_b32_e64 v113, v113, v121, s[6:7]
	v_cndmask_b32_e32 v121, 0, v212, vcc
	v_cmp_gt_f32_e32 vcc, s10, v118
	v_sub_f32_e32 v113, v113, v121
	v_add_f32_e32 v119, 1.0, v119
	v_cndmask_b32_e64 v121, 0, 32, vcc
	v_ldexp_f32 v118, v118, v121
	v_log_f32_e32 v118, v118
	v_add_f32_e32 v115, v107, v115
	v_min_f32_e32 v107, 0, v115
	v_mul_f32_e64 v115, |v115|, s70
	v_mul_f32_e32 v121, 0x3f317217, v118
	v_fma_f32 v121, v118, s77, -v121
	v_fmac_f32_e32 v121, 0x3377d1cf, v118
	v_fmac_f32_e32 v121, 0x3f317217, v118
	v_cmp_lt_f32_e64 s[6:7], |v118|, s0
	v_exp_f32_e32 v115, v115
	v_pk_add_f32 v[108:109], v[108:109], v[116:117] neg_lo:[0,1] neg_hi:[0,1]
	v_cndmask_b32_e64 v118, v118, v121, s[6:7]
	v_cndmask_b32_e32 v121, 0, v212, vcc
	v_cmp_gt_f32_e32 vcc, s10, v114
	v_sub_f32_e32 v118, v118, v121
	v_add_f32_e32 v115, 1.0, v115
	v_cndmask_b32_e64 v121, 0, 32, vcc
	v_ldexp_f32 v114, v114, v121
	v_log_f32_e32 v114, v114
	v_pk_mul_f32 v[108:109], v[108:109], s[2:3] op_sel_hi:[1,0]
	v_pk_add_f32 v[104:105], v[104:105], v[112:113] neg_lo:[0,1] neg_hi:[0,1]
	v_lshl_add_u64 v[112:113], v[122:123], 0, v[172:173]
	v_mul_f32_e32 v121, 0x3f317217, v114
	v_fma_f32 v121, v114, s77, -v121
	v_fmac_f32_e32 v121, 0x3377d1cf, v114
	v_fmac_f32_e32 v121, 0x3f317217, v114
	v_cmp_lt_f32_e64 s[6:7], |v114|, s0
	v_pk_mul_f32 v[104:105], v[104:105], s[2:3] op_sel_hi:[1,0]
	s_nop 0
	v_cndmask_b32_e64 v114, v114, v121, s[6:7]
	v_cndmask_b32_e32 v121, 0, v212, vcc
	v_cmp_gt_f32_e32 vcc, s10, v119
	v_sub_f32_e32 v114, v114, v121
	s_nop 0
	v_cndmask_b32_e64 v121, 0, 32, vcc
	v_ldexp_f32 v119, v119, v121
	v_log_f32_e32 v119, v119
	s_nop 0
	v_mul_f32_e32 v121, 0x3f317217, v119
	v_fma_f32 v121, v119, s77, -v121
	v_fmac_f32_e32 v121, 0x3377d1cf, v119
	v_fmac_f32_e32 v121, 0x3f317217, v119
	v_cmp_lt_f32_e64 s[6:7], |v119|, s0
	s_nop 1
	v_cndmask_b32_e64 v119, v119, v121, s[6:7]
	v_cndmask_b32_e32 v121, 0, v212, vcc
	v_cmp_gt_f32_e32 vcc, s10, v115
	v_sub_f32_e32 v119, v119, v121
	v_pk_add_f32 v[110:111], v[110:111], v[118:119] neg_lo:[0,1] neg_hi:[0,1]
	v_cndmask_b32_e64 v116, 0, 32, vcc
	v_ldexp_f32 v115, v115, v116
	v_log_f32_e32 v115, v115
	v_pk_mul_f32 v[110:111], v[110:111], s[2:3] op_sel_hi:[1,0]
	v_mul_f32_e32 v116, 0x3f317217, v115
	v_fma_f32 v116, v115, s77, -v116
	v_fmac_f32_e32 v116, 0x3377d1cf, v115
	v_fmac_f32_e32 v116, 0x3f317217, v115
	v_cmp_lt_f32_e64 s[6:7], |v115|, s0
	s_nop 1
	v_cndmask_b32_e64 v115, v115, v116, s[6:7]
	v_cndmask_b32_e32 v116, 0, v212, vcc
	v_sub_f32_e32 v115, v115, v116
	v_pk_add_f32 v[106:107], v[106:107], v[114:115] neg_lo:[0,1] neg_hi:[0,1]
	s_nop 0
	v_pk_mul_f32 v[106:107], v[106:107], s[2:3] op_sel_hi:[1,0]
	global_store_dwordx4 v[112:113], v[108:111], off
	global_store_dwordx4 v[112:113], v[104:107], off offset:16

.LBB0_751:
	s_and_b64 vcc, exec, s[0:1]
	s_cbranch_vccz .LBB0_753
	s_lshl_b32 s0, s36, 2
	s_add_u32 s0, s69, s0
	s_addc_u32 s1, s88, 0
	v_mov_b64_e32 v[104:105], v[222:223]
	v_mov_b64_e32 v[106:107], v[224:225]
	v_mov_b64_e32 v[108:109], v[226:227]
	v_mov_b64_e32 v[110:111], v[228:229]
	s_mov_b32 s0, 0x7f800000
	s_mov_b32 s2, 0x3d800000
	v_mov_b32_e32 v173, v177
	v_add_f32_e32 v104, v96, v104
	v_add_f32_e32 v108, v100, v108
	v_min_f32_e32 v100, 0, v108
	v_mul_f32_e64 v108, |v108|, s70
	v_exp_f32_e32 v108, v108
	v_min_f32_e32 v96, 0, v104
	v_mul_f32_e64 v104, |v104|, s70
	v_exp_f32_e32 v104, v104
	v_add_f32_e32 v108, 1.0, v108
	v_cmp_gt_f32_e32 vcc, s10, v108
	v_add_f32_e32 v109, v101, v109
	v_add_f32_e32 v104, 1.0, v104
	v_cndmask_b32_e64 v112, 0, 32, vcc
	v_ldexp_f32 v108, v108, v112
	v_log_f32_e32 v108, v108
	v_min_f32_e32 v101, 0, v109
	v_mul_f32_e64 v109, |v109|, s70
	v_exp_f32_e32 v109, v109
	v_mul_f32_e32 v112, 0x3f317217, v108
	v_fma_f32 v112, v108, s77, -v112
	v_fmac_f32_e32 v112, 0x3377d1cf, v108
	v_fmac_f32_e32 v112, 0x3f317217, v108
	v_cmp_lt_f32_e64 s[6:7], |v108|, s0
	v_add_f32_e32 v109, 1.0, v109
	v_add_f32_e32 v105, v97, v105
	v_cndmask_b32_e64 v108, v108, v112, s[6:7]
	v_cndmask_b32_e32 v112, 0, v212, vcc
	v_cmp_gt_f32_e32 vcc, s10, v104
	v_sub_f32_e32 v108, v108, v112
	v_min_f32_e32 v97, 0, v105
	v_cndmask_b32_e64 v112, 0, 32, vcc
	v_ldexp_f32 v104, v104, v112
	v_log_f32_e32 v104, v104
	v_mul_f32_e64 v105, |v105|, s70
	v_exp_f32_e32 v105, v105
	v_add_f32_e32 v110, v102, v110
	v_mul_f32_e32 v112, 0x3f317217, v104
	v_fma_f32 v112, v104, s77, -v112
	v_fmac_f32_e32 v112, 0x3377d1cf, v104
	v_fmac_f32_e32 v112, 0x3f317217, v104
	v_cmp_lt_f32_e64 s[6:7], |v104|, s0
	v_add_f32_e32 v105, 1.0, v105
	v_min_f32_e32 v102, 0, v110
	v_cndmask_b32_e64 v104, v104, v112, s[6:7]
	v_cndmask_b32_e32 v112, 0, v212, vcc
	v_cmp_gt_f32_e32 vcc, s10, v109
	v_sub_f32_e32 v104, v104, v112
	v_mul_f32_e64 v110, |v110|, s70
	v_cndmask_b32_e64 v112, 0, 32, vcc
	v_ldexp_f32 v109, v109, v112
	v_log_f32_e32 v109, v109
	v_exp_f32_e32 v110, v110
	v_add_f32_e32 v106, v98, v106
	v_min_f32_e32 v98, 0, v106
	v_mul_f32_e32 v112, 0x3f317217, v109
	v_fma_f32 v112, v109, s77, -v112
	v_fmac_f32_e32 v112, 0x3377d1cf, v109
	v_fmac_f32_e32 v112, 0x3f317217, v109
	v_cmp_lt_f32_e64 s[6:7], |v109|, s0
	v_add_f32_e32 v110, 1.0, v110
	v_mul_f32_e64 v106, |v106|, s70
	v_cndmask_b32_e64 v109, v109, v112, s[6:7]
	v_cndmask_b32_e32 v112, 0, v212, vcc
	v_cmp_gt_f32_e32 vcc, s10, v105
	v_sub_f32_e32 v109, v109, v112
	v_exp_f32_e32 v106, v106
	v_cndmask_b32_e64 v112, 0, 32, vcc
	v_ldexp_f32 v105, v105, v112
	v_log_f32_e32 v105, v105
	v_add_f32_e32 v106, 1.0, v106
	v_add_f32_e32 v111, v103, v111
	v_min_f32_e32 v103, 0, v111
	v_mul_f32_e32 v112, 0x3f317217, v105
	v_fma_f32 v112, v105, s77, -v112
	v_fmac_f32_e32 v112, 0x3377d1cf, v105
	v_fmac_f32_e32 v112, 0x3f317217, v105
	v_cmp_lt_f32_e64 s[6:7], |v105|, s0
	v_mul_f32_e64 v111, |v111|, s70
	v_exp_f32_e32 v111, v111
	v_cndmask_b32_e64 v105, v105, v112, s[6:7]
	v_cndmask_b32_e32 v112, 0, v212, vcc
	v_cmp_gt_f32_e32 vcc, s10, v110
	v_sub_f32_e32 v105, v105, v112
	v_add_f32_e32 v111, 1.0, v111
	v_cndmask_b32_e64 v112, 0, 32, vcc
	v_ldexp_f32 v110, v110, v112
	v_log_f32_e32 v110, v110
	v_add_f32_e32 v107, v99, v107
	v_min_f32_e32 v99, 0, v107
	v_mul_f32_e64 v107, |v107|, s70
	v_mul_f32_e32 v112, 0x3f317217, v110
	v_fma_f32 v112, v110, s77, -v112
	v_fmac_f32_e32 v112, 0x3377d1cf, v110
	v_fmac_f32_e32 v112, 0x3f317217, v110
	v_cmp_lt_f32_e64 s[6:7], |v110|, s0
	v_exp_f32_e32 v107, v107
	v_pk_add_f32 v[100:101], v[100:101], v[108:109] neg_lo:[0,1] neg_hi:[0,1]
	v_cndmask_b32_e64 v110, v110, v112, s[6:7]
	v_cndmask_b32_e32 v112, 0, v212, vcc
	v_cmp_gt_f32_e32 vcc, s10, v106
	v_sub_f32_e32 v110, v110, v112
	v_add_f32_e32 v107, 1.0, v107
	v_cndmask_b32_e64 v112, 0, 32, vcc
	v_ldexp_f32 v106, v106, v112
	v_log_f32_e32 v106, v106
	v_pk_mul_f32 v[100:101], v[100:101], s[2:3] op_sel_hi:[1,0]
	v_pk_add_f32 v[96:97], v[96:97], v[104:105] neg_lo:[0,1] neg_hi:[0,1]
	v_lshl_add_u64 v[104:105], v[122:123], 0, v[172:173]
	v_mul_f32_e32 v112, 0x3f317217, v106
	v_fma_f32 v112, v106, s77, -v112
	v_fmac_f32_e32 v112, 0x3377d1cf, v106
	v_fmac_f32_e32 v112, 0x3f317217, v106
	v_cmp_lt_f32_e64 s[6:7], |v106|, s0
	v_pk_mul_f32 v[96:97], v[96:97], s[2:3] op_sel_hi:[1,0]
	s_nop 0
	v_cndmask_b32_e64 v106, v106, v112, s[6:7]
	v_cndmask_b32_e32 v112, 0, v212, vcc
	v_cmp_gt_f32_e32 vcc, s10, v111
	v_sub_f32_e32 v106, v106, v112
	s_nop 0
	v_cndmask_b32_e64 v112, 0, 32, vcc
	v_ldexp_f32 v111, v111, v112
	v_log_f32_e32 v111, v111
	s_nop 0
	v_mul_f32_e32 v112, 0x3f317217, v111
	v_fma_f32 v112, v111, s77, -v112
	v_fmac_f32_e32 v112, 0x3377d1cf, v111
	v_fmac_f32_e32 v112, 0x3f317217, v111
	v_cmp_lt_f32_e64 s[6:7], |v111|, s0
	s_nop 1
	v_cndmask_b32_e64 v111, v111, v112, s[6:7]
	v_cndmask_b32_e32 v112, 0, v212, vcc
	v_cmp_gt_f32_e32 vcc, s10, v107
	v_sub_f32_e32 v111, v111, v112
	v_pk_add_f32 v[102:103], v[102:103], v[110:111] neg_lo:[0,1] neg_hi:[0,1]
	v_cndmask_b32_e64 v108, 0, 32, vcc
	v_ldexp_f32 v107, v107, v108
	v_log_f32_e32 v107, v107
	v_pk_mul_f32 v[102:103], v[102:103], s[2:3] op_sel_hi:[1,0]
	v_mul_f32_e32 v108, 0x3f317217, v107
	v_fma_f32 v108, v107, s77, -v108
	v_fmac_f32_e32 v108, 0x3377d1cf, v107
	v_fmac_f32_e32 v108, 0x3f317217, v107
	v_cmp_lt_f32_e64 s[6:7], |v107|, s0
	s_nop 1
	v_cndmask_b32_e64 v107, v107, v108, s[6:7]
	v_cndmask_b32_e32 v108, 0, v212, vcc
	v_sub_f32_e32 v107, v107, v108
	v_pk_add_f32 v[98:99], v[98:99], v[106:107] neg_lo:[0,1] neg_hi:[0,1]
	s_nop 0
	v_pk_mul_f32 v[98:99], v[98:99], s[2:3] op_sel_hi:[1,0]
	global_store_dwordx4 v[104:105], v[100:103], off offset:512
	global_store_dwordx4 v[104:105], v[96:99], off offset:528

.LBB0_776:
	s_nop 1
	v_lshlrev_b64 v[96:97], 10, v[104:105]
	s_and_b64 vcc, exec, s[0:1]
	v_lshl_add_u64 v[104:105], s[8:9], 0, v[96:97]
	s_cbranch_vccz .LBB0_778
	s_lshl_b32 s0, s36, 2
	s_add_u32 s0, s67, s0
	s_addc_u32 s1, s68, 0
	v_mov_b64_e32 v[96:97], v[214:215]
	v_mov_b64_e32 v[98:99], v[216:217]
	v_mov_b64_e32 v[100:101], v[218:219]
	v_mov_b64_e32 v[102:103], v[220:221]
	s_mov_b32 s0, 0x7f800000
	s_mov_b32 s2, 0x3d800000
	v_mov_b32_e32 v173, v177
	v_add_f32_e32 v96, v88, v96
	v_add_f32_e32 v100, v92, v100
	v_min_f32_e32 v92, 0, v100
	v_mul_f32_e64 v100, |v100|, s70
	v_exp_f32_e32 v100, v100
	v_min_f32_e32 v88, 0, v96
	v_mul_f32_e64 v96, |v96|, s70
	v_exp_f32_e32 v96, v96
	v_add_f32_e32 v100, 1.0, v100
	v_cmp_gt_f32_e32 vcc, s10, v100
	v_add_f32_e32 v101, v93, v101
	v_add_f32_e32 v96, 1.0, v96
	v_cndmask_b32_e64 v111, 0, 32, vcc
	v_ldexp_f32 v100, v100, v111
	v_log_f32_e32 v100, v100
	v_min_f32_e32 v93, 0, v101
	v_mul_f32_e64 v101, |v101|, s70
	v_exp_f32_e32 v101, v101
	v_mul_f32_e32 v111, 0x3f317217, v100
	v_fma_f32 v111, v100, s77, -v111
	v_fmac_f32_e32 v111, 0x3377d1cf, v100
	v_fmac_f32_e32 v111, 0x3f317217, v100
	v_cmp_lt_f32_e64 s[4:5], |v100|, s0
	v_add_f32_e32 v101, 1.0, v101
	v_add_f32_e32 v97, v89, v97
	v_cndmask_b32_e64 v100, v100, v111, s[4:5]
	v_cndmask_b32_e32 v111, 0, v212, vcc
	v_cmp_gt_f32_e32 vcc, s10, v96
	v_sub_f32_e32 v100, v100, v111
	v_min_f32_e32 v89, 0, v97
	v_cndmask_b32_e64 v111, 0, 32, vcc
	v_ldexp_f32 v96, v96, v111
	v_log_f32_e32 v96, v96
	v_mul_f32_e64 v97, |v97|, s70
	v_exp_f32_e32 v97, v97
	v_add_f32_e32 v102, v94, v102
	v_mul_f32_e32 v111, 0x3f317217, v96
	v_fma_f32 v111, v96, s77, -v111
	v_fmac_f32_e32 v111, 0x3377d1cf, v96
	v_fmac_f32_e32 v111, 0x3f317217, v96
	v_cmp_lt_f32_e64 s[4:5], |v96|, s0
	v_add_f32_e32 v97, 1.0, v97
	v_min_f32_e32 v94, 0, v102
	v_cndmask_b32_e64 v96, v96, v111, s[4:5]
	v_cndmask_b32_e32 v111, 0, v212, vcc
	v_cmp_gt_f32_e32 vcc, s10, v101
	v_sub_f32_e32 v96, v96, v111
	v_mul_f32_e64 v102, |v102|, s70
	v_cndmask_b32_e64 v111, 0, 32, vcc
	v_ldexp_f32 v101, v101, v111
	v_log_f32_e32 v101, v101
	v_exp_f32_e32 v102, v102
	v_add_f32_e32 v98, v90, v98
	v_min_f32_e32 v90, 0, v98
	v_mul_f32_e32 v111, 0x3f317217, v101
	v_fma_f32 v111, v101, s77, -v111
	v_fmac_f32_e32 v111, 0x3377d1cf, v101
	v_fmac_f32_e32 v111, 0x3f317217, v101
	v_cmp_lt_f32_e64 s[4:5], |v101|, s0
	v_add_f32_e32 v102, 1.0, v102
	v_mul_f32_e64 v98, |v98|, s70
	v_cndmask_b32_e64 v101, v101, v111, s[4:5]
	v_cndmask_b32_e32 v111, 0, v212, vcc
	v_cmp_gt_f32_e32 vcc, s10, v97
	v_sub_f32_e32 v101, v101, v111
	v_exp_f32_e32 v98, v98
	v_cndmask_b32_e64 v111, 0, 32, vcc
	v_ldexp_f32 v97, v97, v111
	v_log_f32_e32 v97, v97
	v_add_f32_e32 v98, 1.0, v98
	v_add_f32_e32 v103, v95, v103
	v_min_f32_e32 v95, 0, v103
	v_mul_f32_e32 v111, 0x3f317217, v97
	v_fma_f32 v111, v97, s77, -v111
	v_fmac_f32_e32 v111, 0x3377d1cf, v97
	v_fmac_f32_e32 v111, 0x3f317217, v97
	v_cmp_lt_f32_e64 s[4:5], |v97|, s0
	v_mul_f32_e64 v103, |v103|, s70
	v_exp_f32_e32 v103, v103
	v_cndmask_b32_e64 v97, v97, v111, s[4:5]
	v_cndmask_b32_e32 v111, 0, v212, vcc
	v_cmp_gt_f32_e32 vcc, s10, v102
	v_sub_f32_e32 v97, v97, v111
	v_add_f32_e32 v103, 1.0, v103
	v_cndmask_b32_e64 v111, 0, 32, vcc
	v_ldexp_f32 v102, v102, v111
	v_log_f32_e32 v102, v102
	v_add_f32_e32 v99, v91, v99
	v_min_f32_e32 v91, 0, v99
	v_mul_f32_e64 v99, |v99|, s70
	v_mul_f32_e32 v111, 0x3f317217, v102
	v_fma_f32 v111, v102, s77, -v111
	v_fmac_f32_e32 v111, 0x3377d1cf, v102
	v_fmac_f32_e32 v111, 0x3f317217, v102
	v_cmp_lt_f32_e64 s[4:5], |v102|, s0
	v_exp_f32_e32 v99, v99
	v_pk_add_f32 v[92:93], v[92:93], v[100:101] neg_lo:[0,1] neg_hi:[0,1]
	v_cndmask_b32_e64 v102, v102, v111, s[4:5]
	v_cndmask_b32_e32 v111, 0, v212, vcc
	v_cmp_gt_f32_e32 vcc, s10, v98
	v_sub_f32_e32 v102, v102, v111
	v_add_f32_e32 v99, 1.0, v99
	v_cndmask_b32_e64 v111, 0, 32, vcc
	v_ldexp_f32 v98, v98, v111
	v_log_f32_e32 v98, v98
	v_pk_mul_f32 v[92:93], v[92:93], s[2:3] op_sel_hi:[1,0]
	v_pk_add_f32 v[88:89], v[88:89], v[96:97] neg_lo:[0,1] neg_hi:[0,1]
	v_lshl_add_u64 v[96:97], v[104:105], 0, v[172:173]
	v_mul_f32_e32 v111, 0x3f317217, v98
	v_fma_f32 v111, v98, s77, -v111
	v_fmac_f32_e32 v111, 0x3377d1cf, v98
	v_fmac_f32_e32 v111, 0x3f317217, v98
	v_cmp_lt_f32_e64 s[4:5], |v98|, s0
	v_pk_mul_f32 v[88:89], v[88:89], s[2:3] op_sel_hi:[1,0]
	s_nop 0
	v_cndmask_b32_e64 v98, v98, v111, s[4:5]
	v_cndmask_b32_e32 v111, 0, v212, vcc
	v_cmp_gt_f32_e32 vcc, s10, v103
	v_sub_f32_e32 v98, v98, v111
	s_nop 0
	v_cndmask_b32_e64 v111, 0, 32, vcc
	v_ldexp_f32 v103, v103, v111
	v_log_f32_e32 v103, v103
	s_nop 0
	v_mul_f32_e32 v111, 0x3f317217, v103
	v_fma_f32 v111, v103, s77, -v111
	v_fmac_f32_e32 v111, 0x3377d1cf, v103
	v_fmac_f32_e32 v111, 0x3f317217, v103
	v_cmp_lt_f32_e64 s[4:5], |v103|, s0
	s_nop 1
	v_cndmask_b32_e64 v103, v103, v111, s[4:5]
	v_cndmask_b32_e32 v111, 0, v212, vcc
	v_cmp_gt_f32_e32 vcc, s10, v99
	v_sub_f32_e32 v103, v103, v111
	v_pk_add_f32 v[94:95], v[94:95], v[102:103] neg_lo:[0,1] neg_hi:[0,1]
	v_cndmask_b32_e64 v100, 0, 32, vcc
	v_ldexp_f32 v99, v99, v100
	v_log_f32_e32 v99, v99
	v_pk_mul_f32 v[94:95], v[94:95], s[2:3] op_sel_hi:[1,0]
	v_mul_f32_e32 v100, 0x3f317217, v99
	v_fma_f32 v100, v99, s77, -v100
	v_fmac_f32_e32 v100, 0x3377d1cf, v99
	v_fmac_f32_e32 v100, 0x3f317217, v99
	v_cmp_lt_f32_e64 s[4:5], |v99|, s0
	s_nop 1
	v_cndmask_b32_e64 v99, v99, v100, s[4:5]
	v_cndmask_b32_e32 v100, 0, v212, vcc
	v_sub_f32_e32 v99, v99, v100
	v_pk_add_f32 v[90:91], v[90:91], v[98:99] neg_lo:[0,1] neg_hi:[0,1]
	s_nop 0
	v_pk_mul_f32 v[90:91], v[90:91], s[2:3] op_sel_hi:[1,0]
	global_store_dwordx4 v[96:97], v[92:95], off
	global_store_dwordx4 v[96:97], v[88:91], off offset:16

.LBB0_791:
	s_and_b64 vcc, exec, s[0:1]
	s_cbranch_vccz .LBB0_793
	s_lshl_b32 s0, s36, 2
	s_add_u32 s0, s69, s0
	s_addc_u32 s1, s88, 0
	v_mov_b64_e32 v[88:89], v[222:223]
	v_mov_b64_e32 v[90:91], v[224:225]
	v_mov_b64_e32 v[92:93], v[226:227]
	v_mov_b64_e32 v[94:95], v[228:229]
	s_mov_b32 s0, 0x7f800000
	s_mov_b32 s2, 0x3d800000
	v_mov_b32_e32 v173, v177
	v_add_f32_e32 v88, v80, v88
	v_add_f32_e32 v92, v84, v92
	v_min_f32_e32 v84, 0, v92
	v_mul_f32_e64 v92, |v92|, s70
	v_exp_f32_e32 v92, v92
	v_min_f32_e32 v80, 0, v88
	v_mul_f32_e64 v88, |v88|, s70
	v_exp_f32_e32 v88, v88
	v_add_f32_e32 v92, 1.0, v92
	v_cmp_gt_f32_e32 vcc, s10, v92
	v_add_f32_e32 v93, v85, v93
	v_add_f32_e32 v88, 1.0, v88
	v_cndmask_b32_e64 v96, 0, 32, vcc
	v_ldexp_f32 v92, v92, v96
	v_log_f32_e32 v92, v92
	v_min_f32_e32 v85, 0, v93
	v_mul_f32_e64 v93, |v93|, s70
	v_exp_f32_e32 v93, v93
	v_mul_f32_e32 v96, 0x3f317217, v92
	v_fma_f32 v96, v92, s77, -v96
	v_fmac_f32_e32 v96, 0x3377d1cf, v92
	v_fmac_f32_e32 v96, 0x3f317217, v92
	v_cmp_lt_f32_e64 s[4:5], |v92|, s0
	v_add_f32_e32 v93, 1.0, v93
	v_add_f32_e32 v89, v81, v89
	v_cndmask_b32_e64 v92, v92, v96, s[4:5]
	v_cndmask_b32_e32 v96, 0, v212, vcc
	v_cmp_gt_f32_e32 vcc, s10, v88
	v_sub_f32_e32 v92, v92, v96
	v_min_f32_e32 v81, 0, v89
	v_cndmask_b32_e64 v96, 0, 32, vcc
	v_ldexp_f32 v88, v88, v96
	v_log_f32_e32 v88, v88
	v_mul_f32_e64 v89, |v89|, s70
	v_exp_f32_e32 v89, v89
	v_add_f32_e32 v94, v86, v94
	v_mul_f32_e32 v96, 0x3f317217, v88
	v_fma_f32 v96, v88, s77, -v96
	v_fmac_f32_e32 v96, 0x3377d1cf, v88
	v_fmac_f32_e32 v96, 0x3f317217, v88
	v_cmp_lt_f32_e64 s[4:5], |v88|, s0
	v_add_f32_e32 v89, 1.0, v89
	v_min_f32_e32 v86, 0, v94
	v_cndmask_b32_e64 v88, v88, v96, s[4:5]
	v_cndmask_b32_e32 v96, 0, v212, vcc
	v_cmp_gt_f32_e32 vcc, s10, v93
	v_sub_f32_e32 v88, v88, v96
	v_mul_f32_e64 v94, |v94|, s70
	v_cndmask_b32_e64 v96, 0, 32, vcc
	v_ldexp_f32 v93, v93, v96
	v_log_f32_e32 v93, v93
	v_exp_f32_e32 v94, v94
	v_add_f32_e32 v90, v82, v90
	v_min_f32_e32 v82, 0, v90
	v_mul_f32_e32 v96, 0x3f317217, v93
	v_fma_f32 v96, v93, s77, -v96
	v_fmac_f32_e32 v96, 0x3377d1cf, v93
	v_fmac_f32_e32 v96, 0x3f317217, v93
	v_cmp_lt_f32_e64 s[4:5], |v93|, s0
	v_add_f32_e32 v94, 1.0, v94
	v_mul_f32_e64 v90, |v90|, s70
	v_cndmask_b32_e64 v93, v93, v96, s[4:5]
	v_cndmask_b32_e32 v96, 0, v212, vcc
	v_cmp_gt_f32_e32 vcc, s10, v89
	v_sub_f32_e32 v93, v93, v96
	v_exp_f32_e32 v90, v90
	v_cndmask_b32_e64 v96, 0, 32, vcc
	v_ldexp_f32 v89, v89, v96
	v_log_f32_e32 v89, v89
	v_add_f32_e32 v90, 1.0, v90
	v_add_f32_e32 v95, v87, v95
	v_min_f32_e32 v87, 0, v95
	v_mul_f32_e32 v96, 0x3f317217, v89
	v_fma_f32 v96, v89, s77, -v96
	v_fmac_f32_e32 v96, 0x3377d1cf, v89
	v_fmac_f32_e32 v96, 0x3f317217, v89
	v_cmp_lt_f32_e64 s[4:5], |v89|, s0
	v_mul_f32_e64 v95, |v95|, s70
	v_exp_f32_e32 v95, v95
	v_cndmask_b32_e64 v89, v89, v96, s[4:5]
	v_cndmask_b32_e32 v96, 0, v212, vcc
	v_cmp_gt_f32_e32 vcc, s10, v94
	v_sub_f32_e32 v89, v89, v96
	v_add_f32_e32 v95, 1.0, v95
	v_cndmask_b32_e64 v96, 0, 32, vcc
	v_ldexp_f32 v94, v94, v96
	v_log_f32_e32 v94, v94
	v_add_f32_e32 v91, v83, v91
	v_min_f32_e32 v83, 0, v91
	v_mul_f32_e64 v91, |v91|, s70
	v_mul_f32_e32 v96, 0x3f317217, v94
	v_fma_f32 v96, v94, s77, -v96
	v_fmac_f32_e32 v96, 0x3377d1cf, v94
	v_fmac_f32_e32 v96, 0x3f317217, v94
	v_cmp_lt_f32_e64 s[4:5], |v94|, s0
	v_exp_f32_e32 v91, v91
	v_pk_add_f32 v[84:85], v[84:85], v[92:93] neg_lo:[0,1] neg_hi:[0,1]
	v_cndmask_b32_e64 v94, v94, v96, s[4:5]
	v_cndmask_b32_e32 v96, 0, v212, vcc
	v_cmp_gt_f32_e32 vcc, s10, v90
	v_sub_f32_e32 v94, v94, v96
	v_add_f32_e32 v91, 1.0, v91
	v_cndmask_b32_e64 v96, 0, 32, vcc
	v_ldexp_f32 v90, v90, v96
	v_log_f32_e32 v90, v90
	v_pk_mul_f32 v[84:85], v[84:85], s[2:3] op_sel_hi:[1,0]
	v_pk_add_f32 v[80:81], v[80:81], v[88:89] neg_lo:[0,1] neg_hi:[0,1]
	v_lshl_add_u64 v[88:89], v[104:105], 0, v[172:173]
	v_mul_f32_e32 v96, 0x3f317217, v90
	v_fma_f32 v96, v90, s77, -v96
	v_fmac_f32_e32 v96, 0x3377d1cf, v90
	v_fmac_f32_e32 v96, 0x3f317217, v90
	v_cmp_lt_f32_e64 s[4:5], |v90|, s0
	v_pk_mul_f32 v[80:81], v[80:81], s[2:3] op_sel_hi:[1,0]
	s_nop 0
	v_cndmask_b32_e64 v90, v90, v96, s[4:5]
	v_cndmask_b32_e32 v96, 0, v212, vcc
	v_cmp_gt_f32_e32 vcc, s10, v95
	v_sub_f32_e32 v90, v90, v96
	s_nop 0
	v_cndmask_b32_e64 v96, 0, 32, vcc
	v_ldexp_f32 v95, v95, v96
	v_log_f32_e32 v95, v95
	s_nop 0
	v_mul_f32_e32 v96, 0x3f317217, v95
	v_fma_f32 v96, v95, s77, -v96
	v_fmac_f32_e32 v96, 0x3377d1cf, v95
	v_fmac_f32_e32 v96, 0x3f317217, v95
	v_cmp_lt_f32_e64 s[4:5], |v95|, s0
	s_nop 1
	v_cndmask_b32_e64 v95, v95, v96, s[4:5]
	v_cndmask_b32_e32 v96, 0, v212, vcc
	v_cmp_gt_f32_e32 vcc, s10, v91
	v_sub_f32_e32 v95, v95, v96
	v_pk_add_f32 v[86:87], v[86:87], v[94:95] neg_lo:[0,1] neg_hi:[0,1]
	v_cndmask_b32_e64 v92, 0, 32, vcc
	v_ldexp_f32 v91, v91, v92
	v_log_f32_e32 v91, v91
	v_pk_mul_f32 v[86:87], v[86:87], s[2:3] op_sel_hi:[1,0]
	v_mul_f32_e32 v92, 0x3f317217, v91
	v_fma_f32 v92, v91, s77, -v92
	v_fmac_f32_e32 v92, 0x3377d1cf, v91
	v_fmac_f32_e32 v92, 0x3f317217, v91
	v_cmp_lt_f32_e64 s[4:5], |v91|, s0
	s_nop 1
	v_cndmask_b32_e64 v91, v91, v92, s[4:5]
	v_cndmask_b32_e32 v92, 0, v212, vcc
	v_sub_f32_e32 v91, v91, v92
	v_pk_add_f32 v[82:83], v[82:83], v[90:91] neg_lo:[0,1] neg_hi:[0,1]
	s_nop 0
	v_pk_mul_f32 v[82:83], v[82:83], s[2:3] op_sel_hi:[1,0]
	global_store_dwordx4 v[88:89], v[84:87], off offset:512
	global_store_dwordx4 v[88:89], v[80:83], off offset:528

.LBB0_816:
	s_nop 1
	v_lshlrev_b64 v[72:73], 10, v[82:83]
	s_and_b64 vcc, exec, s[0:1]
	v_lshl_add_u64 v[82:83], s[8:9], 0, v[72:73]
	s_cbranch_vccz .LBB0_818
	s_lshl_b32 s0, s36, 2
	s_add_u32 s0, s67, s0
	s_addc_u32 s1, s68, 0
	v_mov_b64_e32 v[72:73], v[214:215]
	v_mov_b64_e32 v[74:75], v[216:217]
	v_mov_b64_e32 v[76:77], v[218:219]
	v_mov_b64_e32 v[78:79], v[220:221]
	s_mov_b32 s0, 0x7f800000
	s_mov_b32 s2, 0x3d800000
	v_mov_b32_e32 v173, v177
	v_add_f32_e32 v72, v64, v72
	v_add_f32_e32 v76, v68, v76
	v_min_f32_e32 v68, 0, v76
	v_mul_f32_e64 v76, |v76|, s70
	v_exp_f32_e32 v76, v76
	v_min_f32_e32 v64, 0, v72
	v_mul_f32_e64 v72, |v72|, s70
	v_exp_f32_e32 v72, v72
	v_add_f32_e32 v76, 1.0, v76
	v_cmp_gt_f32_e32 vcc, s10, v76
	v_add_f32_e32 v77, v69, v77
	v_add_f32_e32 v72, 1.0, v72
	v_cndmask_b32_e64 v81, 0, 32, vcc
	v_ldexp_f32 v76, v76, v81
	v_log_f32_e32 v76, v76
	v_min_f32_e32 v69, 0, v77
	v_mul_f32_e64 v77, |v77|, s70
	v_exp_f32_e32 v77, v77
	v_mul_f32_e32 v81, 0x3f317217, v76
	v_fma_f32 v81, v76, s77, -v81
	v_fmac_f32_e32 v81, 0x3377d1cf, v76
	v_fmac_f32_e32 v81, 0x3f317217, v76
	v_cmp_lt_f32_e64 s[6:7], |v76|, s0
	v_add_f32_e32 v77, 1.0, v77
	v_add_f32_e32 v73, v65, v73
	v_cndmask_b32_e64 v76, v76, v81, s[6:7]
	v_cndmask_b32_e32 v81, 0, v212, vcc
	v_cmp_gt_f32_e32 vcc, s10, v72
	v_sub_f32_e32 v76, v76, v81
	v_min_f32_e32 v65, 0, v73
	v_cndmask_b32_e64 v81, 0, 32, vcc
	v_ldexp_f32 v72, v72, v81
	v_log_f32_e32 v72, v72
	v_mul_f32_e64 v73, |v73|, s70
	v_exp_f32_e32 v73, v73
	v_add_f32_e32 v78, v70, v78
	v_mul_f32_e32 v81, 0x3f317217, v72
	v_fma_f32 v81, v72, s77, -v81
	v_fmac_f32_e32 v81, 0x3377d1cf, v72
	v_fmac_f32_e32 v81, 0x3f317217, v72
	v_cmp_lt_f32_e64 s[6:7], |v72|, s0
	v_add_f32_e32 v73, 1.0, v73
	v_min_f32_e32 v70, 0, v78
	v_cndmask_b32_e64 v72, v72, v81, s[6:7]
	v_cndmask_b32_e32 v81, 0, v212, vcc
	v_cmp_gt_f32_e32 vcc, s10, v77
	v_sub_f32_e32 v72, v72, v81
	v_mul_f32_e64 v78, |v78|, s70
	v_cndmask_b32_e64 v81, 0, 32, vcc
	v_ldexp_f32 v77, v77, v81
	v_log_f32_e32 v77, v77
	v_exp_f32_e32 v78, v78
	v_add_f32_e32 v74, v66, v74
	v_min_f32_e32 v66, 0, v74
	v_mul_f32_e32 v81, 0x3f317217, v77
	v_fma_f32 v81, v77, s77, -v81
	v_fmac_f32_e32 v81, 0x3377d1cf, v77
	v_fmac_f32_e32 v81, 0x3f317217, v77
	v_cmp_lt_f32_e64 s[6:7], |v77|, s0
	v_add_f32_e32 v78, 1.0, v78
	v_mul_f32_e64 v74, |v74|, s70
	v_cndmask_b32_e64 v77, v77, v81, s[6:7]
	v_cndmask_b32_e32 v81, 0, v212, vcc
	v_cmp_gt_f32_e32 vcc, s10, v73
	v_sub_f32_e32 v77, v77, v81
	v_exp_f32_e32 v74, v74
	v_cndmask_b32_e64 v81, 0, 32, vcc
	v_ldexp_f32 v73, v73, v81
	v_log_f32_e32 v73, v73
	v_add_f32_e32 v74, 1.0, v74
	v_add_f32_e32 v79, v71, v79
	v_min_f32_e32 v71, 0, v79
	v_mul_f32_e32 v81, 0x3f317217, v73
	v_fma_f32 v81, v73, s77, -v81
	v_fmac_f32_e32 v81, 0x3377d1cf, v73
	v_fmac_f32_e32 v81, 0x3f317217, v73
	v_cmp_lt_f32_e64 s[6:7], |v73|, s0
	v_mul_f32_e64 v79, |v79|, s70
	v_exp_f32_e32 v79, v79
	v_cndmask_b32_e64 v73, v73, v81, s[6:7]
	v_cndmask_b32_e32 v81, 0, v212, vcc
	v_cmp_gt_f32_e32 vcc, s10, v78
	v_sub_f32_e32 v73, v73, v81
	v_add_f32_e32 v79, 1.0, v79
	v_cndmask_b32_e64 v81, 0, 32, vcc
	v_ldexp_f32 v78, v78, v81
	v_log_f32_e32 v78, v78
	v_add_f32_e32 v75, v67, v75
	v_min_f32_e32 v67, 0, v75
	v_mul_f32_e64 v75, |v75|, s70
	v_mul_f32_e32 v81, 0x3f317217, v78
	v_fma_f32 v81, v78, s77, -v81
	v_fmac_f32_e32 v81, 0x3377d1cf, v78
	v_fmac_f32_e32 v81, 0x3f317217, v78
	v_cmp_lt_f32_e64 s[6:7], |v78|, s0
	v_exp_f32_e32 v75, v75
	v_pk_add_f32 v[68:69], v[68:69], v[76:77] neg_lo:[0,1] neg_hi:[0,1]
	v_cndmask_b32_e64 v78, v78, v81, s[6:7]
	v_cndmask_b32_e32 v81, 0, v212, vcc
	v_cmp_gt_f32_e32 vcc, s10, v74
	v_sub_f32_e32 v78, v78, v81
	v_add_f32_e32 v75, 1.0, v75
	v_cndmask_b32_e64 v81, 0, 32, vcc
	v_ldexp_f32 v74, v74, v81
	v_log_f32_e32 v74, v74
	v_pk_mul_f32 v[68:69], v[68:69], s[2:3] op_sel_hi:[1,0]
	v_pk_add_f32 v[64:65], v[64:65], v[72:73] neg_lo:[0,1] neg_hi:[0,1]
	v_lshl_add_u64 v[72:73], v[82:83], 0, v[172:173]
	v_mul_f32_e32 v81, 0x3f317217, v74
	v_fma_f32 v81, v74, s77, -v81
	v_fmac_f32_e32 v81, 0x3377d1cf, v74
	v_fmac_f32_e32 v81, 0x3f317217, v74
	v_cmp_lt_f32_e64 s[6:7], |v74|, s0
	v_pk_mul_f32 v[64:65], v[64:65], s[2:3] op_sel_hi:[1,0]
	s_nop 0
	v_cndmask_b32_e64 v74, v74, v81, s[6:7]
	v_cndmask_b32_e32 v81, 0, v212, vcc
	v_cmp_gt_f32_e32 vcc, s10, v79
	v_sub_f32_e32 v74, v74, v81
	s_nop 0
	v_cndmask_b32_e64 v81, 0, 32, vcc
	v_ldexp_f32 v79, v79, v81
	v_log_f32_e32 v79, v79
	s_nop 0
	v_mul_f32_e32 v81, 0x3f317217, v79
	v_fma_f32 v81, v79, s77, -v81
	v_fmac_f32_e32 v81, 0x3377d1cf, v79
	v_fmac_f32_e32 v81, 0x3f317217, v79
	v_cmp_lt_f32_e64 s[6:7], |v79|, s0
	s_nop 1
	v_cndmask_b32_e64 v79, v79, v81, s[6:7]
	v_cndmask_b32_e32 v81, 0, v212, vcc
	v_cmp_gt_f32_e32 vcc, s10, v75
	v_sub_f32_e32 v79, v79, v81
	v_pk_add_f32 v[70:71], v[70:71], v[78:79] neg_lo:[0,1] neg_hi:[0,1]
	v_cndmask_b32_e64 v76, 0, 32, vcc
	v_ldexp_f32 v75, v75, v76
	v_log_f32_e32 v75, v75
	v_pk_mul_f32 v[70:71], v[70:71], s[2:3] op_sel_hi:[1,0]
	v_mul_f32_e32 v76, 0x3f317217, v75
	v_fma_f32 v76, v75, s77, -v76
	v_fmac_f32_e32 v76, 0x3377d1cf, v75
	v_fmac_f32_e32 v76, 0x3f317217, v75
	v_cmp_lt_f32_e64 s[6:7], |v75|, s0
	s_nop 1
	v_cndmask_b32_e64 v75, v75, v76, s[6:7]
	v_cndmask_b32_e32 v76, 0, v212, vcc
	v_sub_f32_e32 v75, v75, v76
	v_pk_add_f32 v[66:67], v[66:67], v[74:75] neg_lo:[0,1] neg_hi:[0,1]
	s_nop 0
	v_pk_mul_f32 v[66:67], v[66:67], s[2:3] op_sel_hi:[1,0]
	global_store_dwordx4 v[72:73], v[68:71], off
	global_store_dwordx4 v[72:73], v[64:67], off offset:16

.LBB0_831:
	s_and_b64 vcc, exec, s[0:1]
	s_cbranch_vccz .LBB0_833
	s_lshl_b32 s0, s36, 2
	s_add_u32 s0, s69, s0
	s_addc_u32 s1, s88, 0
	v_mov_b64_e32 v[64:65], v[222:223]
	v_mov_b64_e32 v[66:67], v[224:225]
	v_mov_b64_e32 v[68:69], v[226:227]
	v_mov_b64_e32 v[70:71], v[228:229]
	s_mov_b32 s0, 0x7f800000
	s_mov_b32 s2, 0x3d800000
	v_mov_b32_e32 v173, v177
	v_add_f32_e32 v64, v56, v64
	v_add_f32_e32 v68, v60, v68
	v_min_f32_e32 v60, 0, v68
	v_mul_f32_e64 v68, |v68|, s70
	v_exp_f32_e32 v68, v68
	v_min_f32_e32 v56, 0, v64
	v_mul_f32_e64 v64, |v64|, s70
	v_exp_f32_e32 v64, v64
	v_add_f32_e32 v68, 1.0, v68
	v_cmp_gt_f32_e32 vcc, s10, v68
	v_add_f32_e32 v69, v61, v69
	v_add_f32_e32 v64, 1.0, v64
	v_cndmask_b32_e64 v72, 0, 32, vcc
	v_ldexp_f32 v68, v68, v72
	v_log_f32_e32 v68, v68
	v_min_f32_e32 v61, 0, v69
	v_mul_f32_e64 v69, |v69|, s70
	v_exp_f32_e32 v69, v69
	v_mul_f32_e32 v72, 0x3f317217, v68
	v_fma_f32 v72, v68, s77, -v72
	v_fmac_f32_e32 v72, 0x3377d1cf, v68
	v_fmac_f32_e32 v72, 0x3f317217, v68
	v_cmp_lt_f32_e64 s[6:7], |v68|, s0
	v_add_f32_e32 v69, 1.0, v69
	v_add_f32_e32 v65, v57, v65
	v_cndmask_b32_e64 v68, v68, v72, s[6:7]
	v_cndmask_b32_e32 v72, 0, v212, vcc
	v_cmp_gt_f32_e32 vcc, s10, v64
	v_sub_f32_e32 v68, v68, v72
	v_min_f32_e32 v57, 0, v65
	v_cndmask_b32_e64 v72, 0, 32, vcc
	v_ldexp_f32 v64, v64, v72
	v_log_f32_e32 v64, v64
	v_mul_f32_e64 v65, |v65|, s70
	v_exp_f32_e32 v65, v65
	v_add_f32_e32 v70, v62, v70
	v_mul_f32_e32 v72, 0x3f317217, v64
	v_fma_f32 v72, v64, s77, -v72
	v_fmac_f32_e32 v72, 0x3377d1cf, v64
	v_fmac_f32_e32 v72, 0x3f317217, v64
	v_cmp_lt_f32_e64 s[6:7], |v64|, s0
	v_add_f32_e32 v65, 1.0, v65
	v_min_f32_e32 v62, 0, v70
	v_cndmask_b32_e64 v64, v64, v72, s[6:7]
	v_cndmask_b32_e32 v72, 0, v212, vcc
	v_cmp_gt_f32_e32 vcc, s10, v69
	v_sub_f32_e32 v64, v64, v72
	v_mul_f32_e64 v70, |v70|, s70
	v_cndmask_b32_e64 v72, 0, 32, vcc
	v_ldexp_f32 v69, v69, v72
	v_log_f32_e32 v69, v69
	v_exp_f32_e32 v70, v70
	v_add_f32_e32 v66, v58, v66
	v_min_f32_e32 v58, 0, v66
	v_mul_f32_e32 v72, 0x3f317217, v69
	v_fma_f32 v72, v69, s77, -v72
	v_fmac_f32_e32 v72, 0x3377d1cf, v69
	v_fmac_f32_e32 v72, 0x3f317217, v69
	v_cmp_lt_f32_e64 s[6:7], |v69|, s0
	v_add_f32_e32 v70, 1.0, v70
	v_mul_f32_e64 v66, |v66|, s70
	v_cndmask_b32_e64 v69, v69, v72, s[6:7]
	v_cndmask_b32_e32 v72, 0, v212, vcc
	v_cmp_gt_f32_e32 vcc, s10, v65
	v_sub_f32_e32 v69, v69, v72
	v_exp_f32_e32 v66, v66
	v_cndmask_b32_e64 v72, 0, 32, vcc
	v_ldexp_f32 v65, v65, v72
	v_log_f32_e32 v65, v65
	v_add_f32_e32 v66, 1.0, v66
	v_add_f32_e32 v71, v63, v71
	v_min_f32_e32 v63, 0, v71
	v_mul_f32_e32 v72, 0x3f317217, v65
	v_fma_f32 v72, v65, s77, -v72
	v_fmac_f32_e32 v72, 0x3377d1cf, v65
	v_fmac_f32_e32 v72, 0x3f317217, v65
	v_cmp_lt_f32_e64 s[6:7], |v65|, s0
	v_mul_f32_e64 v71, |v71|, s70
	v_exp_f32_e32 v71, v71
	v_cndmask_b32_e64 v65, v65, v72, s[6:7]
	v_cndmask_b32_e32 v72, 0, v212, vcc
	v_cmp_gt_f32_e32 vcc, s10, v70
	v_sub_f32_e32 v65, v65, v72
	v_add_f32_e32 v71, 1.0, v71
	v_cndmask_b32_e64 v72, 0, 32, vcc
	v_ldexp_f32 v70, v70, v72
	v_log_f32_e32 v70, v70
	v_add_f32_e32 v67, v59, v67
	v_min_f32_e32 v59, 0, v67
	v_mul_f32_e64 v67, |v67|, s70
	v_mul_f32_e32 v72, 0x3f317217, v70
	v_fma_f32 v72, v70, s77, -v72
	v_fmac_f32_e32 v72, 0x3377d1cf, v70
	v_fmac_f32_e32 v72, 0x3f317217, v70
	v_cmp_lt_f32_e64 s[6:7], |v70|, s0
	v_exp_f32_e32 v67, v67
	v_pk_add_f32 v[60:61], v[60:61], v[68:69] neg_lo:[0,1] neg_hi:[0,1]
	v_cndmask_b32_e64 v70, v70, v72, s[6:7]
	v_cndmask_b32_e32 v72, 0, v212, vcc
	v_cmp_gt_f32_e32 vcc, s10, v66
	v_sub_f32_e32 v70, v70, v72
	v_add_f32_e32 v67, 1.0, v67
	v_cndmask_b32_e64 v72, 0, 32, vcc
	v_ldexp_f32 v66, v66, v72
	v_log_f32_e32 v66, v66
	v_pk_mul_f32 v[60:61], v[60:61], s[2:3] op_sel_hi:[1,0]
	v_pk_add_f32 v[56:57], v[56:57], v[64:65] neg_lo:[0,1] neg_hi:[0,1]
	v_lshl_add_u64 v[64:65], v[82:83], 0, v[172:173]
	v_mul_f32_e32 v72, 0x3f317217, v66
	v_fma_f32 v72, v66, s77, -v72
	v_fmac_f32_e32 v72, 0x3377d1cf, v66
	v_fmac_f32_e32 v72, 0x3f317217, v66
	v_cmp_lt_f32_e64 s[6:7], |v66|, s0
	v_pk_mul_f32 v[56:57], v[56:57], s[2:3] op_sel_hi:[1,0]
	s_nop 0
	v_cndmask_b32_e64 v66, v66, v72, s[6:7]
	v_cndmask_b32_e32 v72, 0, v212, vcc
	v_cmp_gt_f32_e32 vcc, s10, v71
	v_sub_f32_e32 v66, v66, v72
	s_nop 0
	v_cndmask_b32_e64 v72, 0, 32, vcc
	v_ldexp_f32 v71, v71, v72
	v_log_f32_e32 v71, v71
	s_nop 0
	v_mul_f32_e32 v72, 0x3f317217, v71
	v_fma_f32 v72, v71, s77, -v72
	v_fmac_f32_e32 v72, 0x3377d1cf, v71
	v_fmac_f32_e32 v72, 0x3f317217, v71
	v_cmp_lt_f32_e64 s[6:7], |v71|, s0
	s_nop 1
	v_cndmask_b32_e64 v71, v71, v72, s[6:7]
	v_cndmask_b32_e32 v72, 0, v212, vcc
	v_cmp_gt_f32_e32 vcc, s10, v67
	v_sub_f32_e32 v71, v71, v72
	v_pk_add_f32 v[62:63], v[62:63], v[70:71] neg_lo:[0,1] neg_hi:[0,1]
	v_cndmask_b32_e64 v68, 0, 32, vcc
	v_ldexp_f32 v67, v67, v68
	v_log_f32_e32 v67, v67
	v_pk_mul_f32 v[62:63], v[62:63], s[2:3] op_sel_hi:[1,0]
	v_mul_f32_e32 v68, 0x3f317217, v67
	v_fma_f32 v68, v67, s77, -v68
	v_fmac_f32_e32 v68, 0x3377d1cf, v67
	v_fmac_f32_e32 v68, 0x3f317217, v67
	v_cmp_lt_f32_e64 s[6:7], |v67|, s0
	s_nop 1
	v_cndmask_b32_e64 v67, v67, v68, s[6:7]
	v_cndmask_b32_e32 v68, 0, v212, vcc
	v_sub_f32_e32 v67, v67, v68
	v_pk_add_f32 v[58:59], v[58:59], v[66:67] neg_lo:[0,1] neg_hi:[0,1]
	s_nop 0
	v_pk_mul_f32 v[58:59], v[58:59], s[2:3] op_sel_hi:[1,0]
	global_store_dwordx4 v[64:65], v[60:63], off offset:512
	global_store_dwordx4 v[64:65], v[56:59], off offset:528

.LBB0_856:
	s_nop 1
	v_lshlrev_b64 v[56:57], 10, v[64:65]
	s_and_b64 vcc, exec, s[0:1]
	v_lshl_add_u64 v[64:65], s[8:9], 0, v[56:57]
	s_cbranch_vccz .LBB0_858
	s_lshl_b32 s0, s36, 2
	s_add_u32 s0, s67, s0
	s_addc_u32 s1, s68, 0
	v_mov_b64_e32 v[56:57], v[214:215]
	v_mov_b64_e32 v[58:59], v[216:217]
	v_mov_b64_e32 v[60:61], v[218:219]
	v_mov_b64_e32 v[62:63], v[220:221]
	s_mov_b32 s0, 0x7f800000
	s_mov_b32 s2, 0x3d800000
	v_mov_b32_e32 v173, v177
	v_add_f32_e32 v56, v48, v56
	v_add_f32_e32 v60, v52, v60
	v_min_f32_e32 v52, 0, v60
	v_mul_f32_e64 v60, |v60|, s70
	v_exp_f32_e32 v60, v60
	v_min_f32_e32 v48, 0, v56
	v_mul_f32_e64 v56, |v56|, s70
	v_exp_f32_e32 v56, v56
	v_add_f32_e32 v60, 1.0, v60
	v_cmp_gt_f32_e32 vcc, s10, v60
	v_add_f32_e32 v61, v53, v61
	v_add_f32_e32 v56, 1.0, v56
	v_cndmask_b32_e64 v71, 0, 32, vcc
	v_ldexp_f32 v60, v60, v71
	v_log_f32_e32 v60, v60
	v_min_f32_e32 v53, 0, v61
	v_mul_f32_e64 v61, |v61|, s70
	v_exp_f32_e32 v61, v61
	v_mul_f32_e32 v71, 0x3f317217, v60
	v_fma_f32 v71, v60, s77, -v71
	v_fmac_f32_e32 v71, 0x3377d1cf, v60
	v_fmac_f32_e32 v71, 0x3f317217, v60
	v_cmp_lt_f32_e64 s[4:5], |v60|, s0
	v_add_f32_e32 v61, 1.0, v61
	v_add_f32_e32 v57, v49, v57
	v_cndmask_b32_e64 v60, v60, v71, s[4:5]
	v_cndmask_b32_e32 v71, 0, v212, vcc
	v_cmp_gt_f32_e32 vcc, s10, v56
	v_sub_f32_e32 v60, v60, v71
	v_min_f32_e32 v49, 0, v57
	v_cndmask_b32_e64 v71, 0, 32, vcc
	v_ldexp_f32 v56, v56, v71
	v_log_f32_e32 v56, v56
	v_mul_f32_e64 v57, |v57|, s70
	v_exp_f32_e32 v57, v57
	v_add_f32_e32 v62, v54, v62
	v_mul_f32_e32 v71, 0x3f317217, v56
	v_fma_f32 v71, v56, s77, -v71
	v_fmac_f32_e32 v71, 0x3377d1cf, v56
	v_fmac_f32_e32 v71, 0x3f317217, v56
	v_cmp_lt_f32_e64 s[4:5], |v56|, s0
	v_add_f32_e32 v57, 1.0, v57
	v_min_f32_e32 v54, 0, v62
	v_cndmask_b32_e64 v56, v56, v71, s[4:5]
	v_cndmask_b32_e32 v71, 0, v212, vcc
	v_cmp_gt_f32_e32 vcc, s10, v61
	v_sub_f32_e32 v56, v56, v71
	v_mul_f32_e64 v62, |v62|, s70
	v_cndmask_b32_e64 v71, 0, 32, vcc
	v_ldexp_f32 v61, v61, v71
	v_log_f32_e32 v61, v61
	v_exp_f32_e32 v62, v62
	v_add_f32_e32 v58, v50, v58
	v_min_f32_e32 v50, 0, v58
	v_mul_f32_e32 v71, 0x3f317217, v61
	v_fma_f32 v71, v61, s77, -v71
	v_fmac_f32_e32 v71, 0x3377d1cf, v61
	v_fmac_f32_e32 v71, 0x3f317217, v61
	v_cmp_lt_f32_e64 s[4:5], |v61|, s0
	v_add_f32_e32 v62, 1.0, v62
	v_mul_f32_e64 v58, |v58|, s70
	v_cndmask_b32_e64 v61, v61, v71, s[4:5]
	v_cndmask_b32_e32 v71, 0, v212, vcc
	v_cmp_gt_f32_e32 vcc, s10, v57
	v_sub_f32_e32 v61, v61, v71
	v_exp_f32_e32 v58, v58
	v_cndmask_b32_e64 v71, 0, 32, vcc
	v_ldexp_f32 v57, v57, v71
	v_log_f32_e32 v57, v57
	v_add_f32_e32 v58, 1.0, v58
	v_add_f32_e32 v63, v55, v63
	v_min_f32_e32 v55, 0, v63
	v_mul_f32_e32 v71, 0x3f317217, v57
	v_fma_f32 v71, v57, s77, -v71
	v_fmac_f32_e32 v71, 0x3377d1cf, v57
	v_fmac_f32_e32 v71, 0x3f317217, v57
	v_cmp_lt_f32_e64 s[4:5], |v57|, s0
	v_mul_f32_e64 v63, |v63|, s70
	v_exp_f32_e32 v63, v63
	v_cndmask_b32_e64 v57, v57, v71, s[4:5]
	v_cndmask_b32_e32 v71, 0, v212, vcc
	v_cmp_gt_f32_e32 vcc, s10, v62
	v_sub_f32_e32 v57, v57, v71
	v_add_f32_e32 v63, 1.0, v63
	v_cndmask_b32_e64 v71, 0, 32, vcc
	v_ldexp_f32 v62, v62, v71
	v_log_f32_e32 v62, v62
	v_add_f32_e32 v59, v51, v59
	v_min_f32_e32 v51, 0, v59
	v_mul_f32_e64 v59, |v59|, s70
	v_mul_f32_e32 v71, 0x3f317217, v62
	v_fma_f32 v71, v62, s77, -v71
	v_fmac_f32_e32 v71, 0x3377d1cf, v62
	v_fmac_f32_e32 v71, 0x3f317217, v62
	v_cmp_lt_f32_e64 s[4:5], |v62|, s0
	v_exp_f32_e32 v59, v59
	v_pk_add_f32 v[52:53], v[52:53], v[60:61] neg_lo:[0,1] neg_hi:[0,1]
	v_cndmask_b32_e64 v62, v62, v71, s[4:5]
	v_cndmask_b32_e32 v71, 0, v212, vcc
	v_cmp_gt_f32_e32 vcc, s10, v58
	v_sub_f32_e32 v62, v62, v71
	v_add_f32_e32 v59, 1.0, v59
	v_cndmask_b32_e64 v71, 0, 32, vcc
	v_ldexp_f32 v58, v58, v71
	v_log_f32_e32 v58, v58
	v_pk_mul_f32 v[52:53], v[52:53], s[2:3] op_sel_hi:[1,0]
	v_pk_add_f32 v[48:49], v[48:49], v[56:57] neg_lo:[0,1] neg_hi:[0,1]
	v_lshl_add_u64 v[56:57], v[64:65], 0, v[172:173]
	v_mul_f32_e32 v71, 0x3f317217, v58
	v_fma_f32 v71, v58, s77, -v71
	v_fmac_f32_e32 v71, 0x3377d1cf, v58
	v_fmac_f32_e32 v71, 0x3f317217, v58
	v_cmp_lt_f32_e64 s[4:5], |v58|, s0
	v_pk_mul_f32 v[48:49], v[48:49], s[2:3] op_sel_hi:[1,0]
	s_nop 0
	v_cndmask_b32_e64 v58, v58, v71, s[4:5]
	v_cndmask_b32_e32 v71, 0, v212, vcc
	v_cmp_gt_f32_e32 vcc, s10, v63
	v_sub_f32_e32 v58, v58, v71
	s_nop 0
	v_cndmask_b32_e64 v71, 0, 32, vcc
	v_ldexp_f32 v63, v63, v71
	v_log_f32_e32 v63, v63
	s_nop 0
	v_mul_f32_e32 v71, 0x3f317217, v63
	v_fma_f32 v71, v63, s77, -v71
	v_fmac_f32_e32 v71, 0x3377d1cf, v63
	v_fmac_f32_e32 v71, 0x3f317217, v63
	v_cmp_lt_f32_e64 s[4:5], |v63|, s0
	s_nop 1
	v_cndmask_b32_e64 v63, v63, v71, s[4:5]
	v_cndmask_b32_e32 v71, 0, v212, vcc
	v_cmp_gt_f32_e32 vcc, s10, v59
	v_sub_f32_e32 v63, v63, v71
	v_pk_add_f32 v[54:55], v[54:55], v[62:63] neg_lo:[0,1] neg_hi:[0,1]
	v_cndmask_b32_e64 v60, 0, 32, vcc
	v_ldexp_f32 v59, v59, v60
	v_log_f32_e32 v59, v59
	v_pk_mul_f32 v[54:55], v[54:55], s[2:3] op_sel_hi:[1,0]
	v_mul_f32_e32 v60, 0x3f317217, v59
	v_fma_f32 v60, v59, s77, -v60
	v_fmac_f32_e32 v60, 0x3377d1cf, v59
	v_fmac_f32_e32 v60, 0x3f317217, v59
	v_cmp_lt_f32_e64 s[4:5], |v59|, s0
	s_nop 1
	v_cndmask_b32_e64 v59, v59, v60, s[4:5]
	v_cndmask_b32_e32 v60, 0, v212, vcc
	v_sub_f32_e32 v59, v59, v60
	v_pk_add_f32 v[50:51], v[50:51], v[58:59] neg_lo:[0,1] neg_hi:[0,1]
	s_nop 0
	v_pk_mul_f32 v[50:51], v[50:51], s[2:3] op_sel_hi:[1,0]
	global_store_dwordx4 v[56:57], v[52:55], off
	global_store_dwordx4 v[56:57], v[48:51], off offset:16

.LBB0_871:
	s_and_b64 vcc, exec, s[0:1]
	s_cbranch_vccz .LBB0_873
	s_lshl_b32 s0, s36, 2
	s_add_u32 s0, s69, s0
	s_addc_u32 s1, s88, 0
	v_mov_b64_e32 v[48:49], v[222:223]
	v_mov_b64_e32 v[50:51], v[224:225]
	v_mov_b64_e32 v[52:53], v[226:227]
	v_mov_b64_e32 v[54:55], v[228:229]
	s_mov_b32 s0, 0x7f800000
	s_mov_b32 s2, 0x3d800000
	v_mov_b32_e32 v173, v177
	v_add_f32_e32 v48, v40, v48
	v_add_f32_e32 v52, v44, v52
	v_min_f32_e32 v44, 0, v52
	v_mul_f32_e64 v52, |v52|, s70
	v_exp_f32_e32 v52, v52
	v_min_f32_e32 v40, 0, v48
	v_mul_f32_e64 v48, |v48|, s70
	v_exp_f32_e32 v48, v48
	v_add_f32_e32 v52, 1.0, v52
	v_cmp_gt_f32_e32 vcc, s10, v52
	v_add_f32_e32 v53, v45, v53
	v_add_f32_e32 v48, 1.0, v48
	v_cndmask_b32_e64 v56, 0, 32, vcc
	v_ldexp_f32 v52, v52, v56
	v_log_f32_e32 v52, v52
	v_min_f32_e32 v45, 0, v53
	v_mul_f32_e64 v53, |v53|, s70
	v_exp_f32_e32 v53, v53
	v_mul_f32_e32 v56, 0x3f317217, v52
	v_fma_f32 v56, v52, s77, -v56
	v_fmac_f32_e32 v56, 0x3377d1cf, v52
	v_fmac_f32_e32 v56, 0x3f317217, v52
	v_cmp_lt_f32_e64 s[4:5], |v52|, s0
	v_add_f32_e32 v53, 1.0, v53
	v_add_f32_e32 v49, v41, v49
	v_cndmask_b32_e64 v52, v52, v56, s[4:5]
	v_cndmask_b32_e32 v56, 0, v212, vcc
	v_cmp_gt_f32_e32 vcc, s10, v48
	v_sub_f32_e32 v52, v52, v56
	v_min_f32_e32 v41, 0, v49
	v_cndmask_b32_e64 v56, 0, 32, vcc
	v_ldexp_f32 v48, v48, v56
	v_log_f32_e32 v48, v48
	v_mul_f32_e64 v49, |v49|, s70
	v_exp_f32_e32 v49, v49
	v_add_f32_e32 v54, v46, v54
	v_mul_f32_e32 v56, 0x3f317217, v48
	v_fma_f32 v56, v48, s77, -v56
	v_fmac_f32_e32 v56, 0x3377d1cf, v48
	v_fmac_f32_e32 v56, 0x3f317217, v48
	v_cmp_lt_f32_e64 s[4:5], |v48|, s0
	v_add_f32_e32 v49, 1.0, v49
	v_min_f32_e32 v46, 0, v54
	v_cndmask_b32_e64 v48, v48, v56, s[4:5]
	v_cndmask_b32_e32 v56, 0, v212, vcc
	v_cmp_gt_f32_e32 vcc, s10, v53
	v_sub_f32_e32 v48, v48, v56
	v_mul_f32_e64 v54, |v54|, s70
	v_cndmask_b32_e64 v56, 0, 32, vcc
	v_ldexp_f32 v53, v53, v56
	v_log_f32_e32 v53, v53
	v_exp_f32_e32 v54, v54
	v_add_f32_e32 v50, v42, v50
	v_min_f32_e32 v42, 0, v50
	v_mul_f32_e32 v56, 0x3f317217, v53
	v_fma_f32 v56, v53, s77, -v56
	v_fmac_f32_e32 v56, 0x3377d1cf, v53
	v_fmac_f32_e32 v56, 0x3f317217, v53
	v_cmp_lt_f32_e64 s[4:5], |v53|, s0
	v_add_f32_e32 v54, 1.0, v54
	v_mul_f32_e64 v50, |v50|, s70
	v_cndmask_b32_e64 v53, v53, v56, s[4:5]
	v_cndmask_b32_e32 v56, 0, v212, vcc
	v_cmp_gt_f32_e32 vcc, s10, v49
	v_sub_f32_e32 v53, v53, v56
	v_exp_f32_e32 v50, v50
	v_cndmask_b32_e64 v56, 0, 32, vcc
	v_ldexp_f32 v49, v49, v56
	v_log_f32_e32 v49, v49
	v_add_f32_e32 v50, 1.0, v50
	v_add_f32_e32 v55, v47, v55
	v_min_f32_e32 v47, 0, v55
	v_mul_f32_e32 v56, 0x3f317217, v49
	v_fma_f32 v56, v49, s77, -v56
	v_fmac_f32_e32 v56, 0x3377d1cf, v49
	v_fmac_f32_e32 v56, 0x3f317217, v49
	v_cmp_lt_f32_e64 s[4:5], |v49|, s0
	v_mul_f32_e64 v55, |v55|, s70
	v_exp_f32_e32 v55, v55
	v_cndmask_b32_e64 v49, v49, v56, s[4:5]
	v_cndmask_b32_e32 v56, 0, v212, vcc
	v_cmp_gt_f32_e32 vcc, s10, v54
	v_sub_f32_e32 v49, v49, v56
	v_add_f32_e32 v55, 1.0, v55
	v_cndmask_b32_e64 v56, 0, 32, vcc
	v_ldexp_f32 v54, v54, v56
	v_log_f32_e32 v54, v54
	v_add_f32_e32 v51, v43, v51
	v_min_f32_e32 v43, 0, v51
	v_mul_f32_e64 v51, |v51|, s70
	v_mul_f32_e32 v56, 0x3f317217, v54
	v_fma_f32 v56, v54, s77, -v56
	v_fmac_f32_e32 v56, 0x3377d1cf, v54
	v_fmac_f32_e32 v56, 0x3f317217, v54
	v_cmp_lt_f32_e64 s[4:5], |v54|, s0
	v_exp_f32_e32 v51, v51
	v_pk_add_f32 v[44:45], v[44:45], v[52:53] neg_lo:[0,1] neg_hi:[0,1]
	v_cndmask_b32_e64 v54, v54, v56, s[4:5]
	v_cndmask_b32_e32 v56, 0, v212, vcc
	v_cmp_gt_f32_e32 vcc, s10, v50
	v_sub_f32_e32 v54, v54, v56
	v_add_f32_e32 v51, 1.0, v51
	v_cndmask_b32_e64 v56, 0, 32, vcc
	v_ldexp_f32 v50, v50, v56
	v_log_f32_e32 v50, v50
	v_pk_mul_f32 v[44:45], v[44:45], s[2:3] op_sel_hi:[1,0]
	v_pk_add_f32 v[40:41], v[40:41], v[48:49] neg_lo:[0,1] neg_hi:[0,1]
	v_lshl_add_u64 v[48:49], v[64:65], 0, v[172:173]
	v_mul_f32_e32 v56, 0x3f317217, v50
	v_fma_f32 v56, v50, s77, -v56
	v_fmac_f32_e32 v56, 0x3377d1cf, v50
	v_fmac_f32_e32 v56, 0x3f317217, v50
	v_cmp_lt_f32_e64 s[4:5], |v50|, s0
	v_pk_mul_f32 v[40:41], v[40:41], s[2:3] op_sel_hi:[1,0]
	s_nop 0
	v_cndmask_b32_e64 v50, v50, v56, s[4:5]
	v_cndmask_b32_e32 v56, 0, v212, vcc
	v_cmp_gt_f32_e32 vcc, s10, v55
	v_sub_f32_e32 v50, v50, v56
	s_nop 0
	v_cndmask_b32_e64 v56, 0, 32, vcc
	v_ldexp_f32 v55, v55, v56
	v_log_f32_e32 v55, v55
	s_nop 0
	v_mul_f32_e32 v56, 0x3f317217, v55
	v_fma_f32 v56, v55, s77, -v56
	v_fmac_f32_e32 v56, 0x3377d1cf, v55
	v_fmac_f32_e32 v56, 0x3f317217, v55
	v_cmp_lt_f32_e64 s[4:5], |v55|, s0
	s_nop 1
	v_cndmask_b32_e64 v55, v55, v56, s[4:5]
	v_cndmask_b32_e32 v56, 0, v212, vcc
	v_cmp_gt_f32_e32 vcc, s10, v51
	v_sub_f32_e32 v55, v55, v56
	v_pk_add_f32 v[46:47], v[46:47], v[54:55] neg_lo:[0,1] neg_hi:[0,1]
	v_cndmask_b32_e64 v52, 0, 32, vcc
	v_ldexp_f32 v51, v51, v52
	v_log_f32_e32 v51, v51
	v_pk_mul_f32 v[46:47], v[46:47], s[2:3] op_sel_hi:[1,0]
	v_mul_f32_e32 v52, 0x3f317217, v51
	v_fma_f32 v52, v51, s77, -v52
	v_fmac_f32_e32 v52, 0x3377d1cf, v51
	v_fmac_f32_e32 v52, 0x3f317217, v51
	v_cmp_lt_f32_e64 s[4:5], |v51|, s0
	s_nop 1
	v_cndmask_b32_e64 v51, v51, v52, s[4:5]
	v_cndmask_b32_e32 v52, 0, v212, vcc
	v_sub_f32_e32 v51, v51, v52
	v_pk_add_f32 v[42:43], v[42:43], v[50:51] neg_lo:[0,1] neg_hi:[0,1]
	s_nop 0
	v_pk_mul_f32 v[42:43], v[42:43], s[2:3] op_sel_hi:[1,0]
	global_store_dwordx4 v[48:49], v[44:47], off offset:512
	global_store_dwordx4 v[48:49], v[40:43], off offset:528

.LBB0_896:
	s_nop 1
	v_lshlrev_b64 v[32:33], 10, v[42:43]
	s_and_b64 vcc, exec, s[0:1]
	v_lshl_add_u64 v[42:43], s[8:9], 0, v[32:33]
	s_cbranch_vccz .LBB0_898
	s_lshl_b32 s0, s36, 2
	s_add_u32 s0, s67, s0
	s_addc_u32 s1, s68, 0
	v_mov_b64_e32 v[32:33], v[214:215]
	v_mov_b64_e32 v[34:35], v[216:217]
	v_mov_b64_e32 v[36:37], v[218:219]
	v_mov_b64_e32 v[38:39], v[220:221]
	s_mov_b32 s0, 0x7f800000
	s_mov_b32 s2, 0x3d800000
	v_mov_b32_e32 v173, v177
	v_add_f32_e32 v32, v24, v32
	v_add_f32_e32 v36, v28, v36
	v_min_f32_e32 v28, 0, v36
	v_mul_f32_e64 v36, |v36|, s70
	v_exp_f32_e32 v36, v36
	v_min_f32_e32 v24, 0, v32
	v_mul_f32_e64 v32, |v32|, s70
	v_exp_f32_e32 v32, v32
	v_add_f32_e32 v36, 1.0, v36
	v_cmp_gt_f32_e32 vcc, s10, v36
	v_add_f32_e32 v37, v29, v37
	v_add_f32_e32 v32, 1.0, v32
	v_cndmask_b32_e64 v41, 0, 32, vcc
	v_ldexp_f32 v36, v36, v41
	v_log_f32_e32 v36, v36
	v_min_f32_e32 v29, 0, v37
	v_mul_f32_e64 v37, |v37|, s70
	v_exp_f32_e32 v37, v37
	v_mul_f32_e32 v41, 0x3f317217, v36
	v_fma_f32 v41, v36, s77, -v41
	v_fmac_f32_e32 v41, 0x3377d1cf, v36
	v_fmac_f32_e32 v41, 0x3f317217, v36
	v_cmp_lt_f32_e64 s[6:7], |v36|, s0
	v_add_f32_e32 v37, 1.0, v37
	v_add_f32_e32 v33, v25, v33
	v_cndmask_b32_e64 v36, v36, v41, s[6:7]
	v_cndmask_b32_e32 v41, 0, v212, vcc
	v_cmp_gt_f32_e32 vcc, s10, v32
	v_sub_f32_e32 v36, v36, v41
	v_min_f32_e32 v25, 0, v33
	v_cndmask_b32_e64 v41, 0, 32, vcc
	v_ldexp_f32 v32, v32, v41
	v_log_f32_e32 v32, v32
	v_mul_f32_e64 v33, |v33|, s70
	v_exp_f32_e32 v33, v33
	v_add_f32_e32 v38, v30, v38
	v_mul_f32_e32 v41, 0x3f317217, v32
	v_fma_f32 v41, v32, s77, -v41
	v_fmac_f32_e32 v41, 0x3377d1cf, v32
	v_fmac_f32_e32 v41, 0x3f317217, v32
	v_cmp_lt_f32_e64 s[6:7], |v32|, s0
	v_add_f32_e32 v33, 1.0, v33
	v_min_f32_e32 v30, 0, v38
	v_cndmask_b32_e64 v32, v32, v41, s[6:7]
	v_cndmask_b32_e32 v41, 0, v212, vcc
	v_cmp_gt_f32_e32 vcc, s10, v37
	v_sub_f32_e32 v32, v32, v41
	v_mul_f32_e64 v38, |v38|, s70
	v_cndmask_b32_e64 v41, 0, 32, vcc
	v_ldexp_f32 v37, v37, v41
	v_log_f32_e32 v37, v37
	v_exp_f32_e32 v38, v38
	v_add_f32_e32 v34, v26, v34
	v_min_f32_e32 v26, 0, v34
	v_mul_f32_e32 v41, 0x3f317217, v37
	v_fma_f32 v41, v37, s77, -v41
	v_fmac_f32_e32 v41, 0x3377d1cf, v37
	v_fmac_f32_e32 v41, 0x3f317217, v37
	v_cmp_lt_f32_e64 s[6:7], |v37|, s0
	v_add_f32_e32 v38, 1.0, v38
	v_mul_f32_e64 v34, |v34|, s70
	v_cndmask_b32_e64 v37, v37, v41, s[6:7]
	v_cndmask_b32_e32 v41, 0, v212, vcc
	v_cmp_gt_f32_e32 vcc, s10, v33
	v_sub_f32_e32 v37, v37, v41
	v_exp_f32_e32 v34, v34
	v_cndmask_b32_e64 v41, 0, 32, vcc
	v_ldexp_f32 v33, v33, v41
	v_log_f32_e32 v33, v33
	v_add_f32_e32 v34, 1.0, v34
	v_add_f32_e32 v39, v31, v39
	v_min_f32_e32 v31, 0, v39
	v_mul_f32_e32 v41, 0x3f317217, v33
	v_fma_f32 v41, v33, s77, -v41
	v_fmac_f32_e32 v41, 0x3377d1cf, v33
	v_fmac_f32_e32 v41, 0x3f317217, v33
	v_cmp_lt_f32_e64 s[6:7], |v33|, s0
	v_mul_f32_e64 v39, |v39|, s70
	v_exp_f32_e32 v39, v39
	v_cndmask_b32_e64 v33, v33, v41, s[6:7]
	v_cndmask_b32_e32 v41, 0, v212, vcc
	v_cmp_gt_f32_e32 vcc, s10, v38
	v_sub_f32_e32 v33, v33, v41
	v_add_f32_e32 v39, 1.0, v39
	v_cndmask_b32_e64 v41, 0, 32, vcc
	v_ldexp_f32 v38, v38, v41
	v_log_f32_e32 v38, v38
	v_add_f32_e32 v35, v27, v35
	v_min_f32_e32 v27, 0, v35
	v_mul_f32_e64 v35, |v35|, s70
	v_mul_f32_e32 v41, 0x3f317217, v38
	v_fma_f32 v41, v38, s77, -v41
	v_fmac_f32_e32 v41, 0x3377d1cf, v38
	v_fmac_f32_e32 v41, 0x3f317217, v38
	v_cmp_lt_f32_e64 s[6:7], |v38|, s0
	v_exp_f32_e32 v35, v35
	v_pk_add_f32 v[28:29], v[28:29], v[36:37] neg_lo:[0,1] neg_hi:[0,1]
	v_cndmask_b32_e64 v38, v38, v41, s[6:7]
	v_cndmask_b32_e32 v41, 0, v212, vcc
	v_cmp_gt_f32_e32 vcc, s10, v34
	v_sub_f32_e32 v38, v38, v41
	v_add_f32_e32 v35, 1.0, v35
	v_cndmask_b32_e64 v41, 0, 32, vcc
	v_ldexp_f32 v34, v34, v41
	v_log_f32_e32 v34, v34
	v_pk_mul_f32 v[28:29], v[28:29], s[2:3] op_sel_hi:[1,0]
	v_pk_add_f32 v[24:25], v[24:25], v[32:33] neg_lo:[0,1] neg_hi:[0,1]
	v_lshl_add_u64 v[32:33], v[42:43], 0, v[172:173]
	v_mul_f32_e32 v41, 0x3f317217, v34
	v_fma_f32 v41, v34, s77, -v41
	v_fmac_f32_e32 v41, 0x3377d1cf, v34
	v_fmac_f32_e32 v41, 0x3f317217, v34
	v_cmp_lt_f32_e64 s[6:7], |v34|, s0
	v_pk_mul_f32 v[24:25], v[24:25], s[2:3] op_sel_hi:[1,0]
	s_nop 0
	v_cndmask_b32_e64 v34, v34, v41, s[6:7]
	v_cndmask_b32_e32 v41, 0, v212, vcc
	v_cmp_gt_f32_e32 vcc, s10, v39
	v_sub_f32_e32 v34, v34, v41
	s_nop 0
	v_cndmask_b32_e64 v41, 0, 32, vcc
	v_ldexp_f32 v39, v39, v41
	v_log_f32_e32 v39, v39
	s_nop 0
	v_mul_f32_e32 v41, 0x3f317217, v39
	v_fma_f32 v41, v39, s77, -v41
	v_fmac_f32_e32 v41, 0x3377d1cf, v39
	v_fmac_f32_e32 v41, 0x3f317217, v39
	v_cmp_lt_f32_e64 s[6:7], |v39|, s0
	s_nop 1
	v_cndmask_b32_e64 v39, v39, v41, s[6:7]
	v_cndmask_b32_e32 v41, 0, v212, vcc
	v_cmp_gt_f32_e32 vcc, s10, v35
	v_sub_f32_e32 v39, v39, v41
	v_pk_add_f32 v[30:31], v[30:31], v[38:39] neg_lo:[0,1] neg_hi:[0,1]
	v_cndmask_b32_e64 v36, 0, 32, vcc
	v_ldexp_f32 v35, v35, v36
	v_log_f32_e32 v35, v35
	v_pk_mul_f32 v[30:31], v[30:31], s[2:3] op_sel_hi:[1,0]
	v_mul_f32_e32 v36, 0x3f317217, v35
	v_fma_f32 v36, v35, s77, -v36
	v_fmac_f32_e32 v36, 0x3377d1cf, v35
	v_fmac_f32_e32 v36, 0x3f317217, v35
	v_cmp_lt_f32_e64 s[6:7], |v35|, s0
	s_nop 1
	v_cndmask_b32_e64 v35, v35, v36, s[6:7]
	v_cndmask_b32_e32 v36, 0, v212, vcc
	v_sub_f32_e32 v35, v35, v36
	v_pk_add_f32 v[26:27], v[26:27], v[34:35] neg_lo:[0,1] neg_hi:[0,1]
	s_nop 0
	v_pk_mul_f32 v[26:27], v[26:27], s[2:3] op_sel_hi:[1,0]
	global_store_dwordx4 v[32:33], v[28:31], off
	global_store_dwordx4 v[32:33], v[24:27], off offset:16

.LBB0_911:
	s_and_b64 vcc, exec, s[0:1]
	s_cbranch_vccz .LBB0_913
	s_lshl_b32 s0, s36, 2
	s_add_u32 s0, s69, s0
	s_addc_u32 s1, s88, 0
	v_mov_b64_e32 v[24:25], v[222:223]
	v_mov_b64_e32 v[26:27], v[224:225]
	v_mov_b64_e32 v[28:29], v[226:227]
	v_mov_b64_e32 v[30:31], v[228:229]
	s_mov_b32 s0, 0x7f800000
	s_mov_b32 s2, 0x3d800000
	v_mov_b32_e32 v173, v177
	v_add_f32_e32 v24, v16, v24
	v_add_f32_e32 v28, v20, v28
	v_min_f32_e32 v20, 0, v28
	v_mul_f32_e64 v28, |v28|, s70
	v_exp_f32_e32 v28, v28
	v_min_f32_e32 v16, 0, v24
	v_mul_f32_e64 v24, |v24|, s70
	v_exp_f32_e32 v24, v24
	v_add_f32_e32 v28, 1.0, v28
	v_cmp_gt_f32_e32 vcc, s10, v28
	v_add_f32_e32 v29, v21, v29
	v_add_f32_e32 v24, 1.0, v24
	v_cndmask_b32_e64 v32, 0, 32, vcc
	v_ldexp_f32 v28, v28, v32
	v_log_f32_e32 v28, v28
	v_min_f32_e32 v21, 0, v29
	v_mul_f32_e64 v29, |v29|, s70
	v_exp_f32_e32 v29, v29
	v_mul_f32_e32 v32, 0x3f317217, v28
	v_fma_f32 v32, v28, s77, -v32
	v_fmac_f32_e32 v32, 0x3377d1cf, v28
	v_fmac_f32_e32 v32, 0x3f317217, v28
	v_cmp_lt_f32_e64 s[6:7], |v28|, s0
	v_add_f32_e32 v29, 1.0, v29
	v_add_f32_e32 v25, v17, v25
	v_cndmask_b32_e64 v28, v28, v32, s[6:7]
	v_cndmask_b32_e32 v32, 0, v212, vcc
	v_cmp_gt_f32_e32 vcc, s10, v24
	v_sub_f32_e32 v28, v28, v32
	v_min_f32_e32 v17, 0, v25
	v_cndmask_b32_e64 v32, 0, 32, vcc
	v_ldexp_f32 v24, v24, v32
	v_log_f32_e32 v24, v24
	v_mul_f32_e64 v25, |v25|, s70
	v_exp_f32_e32 v25, v25
	v_add_f32_e32 v30, v22, v30
	v_mul_f32_e32 v32, 0x3f317217, v24
	v_fma_f32 v32, v24, s77, -v32
	v_fmac_f32_e32 v32, 0x3377d1cf, v24
	v_fmac_f32_e32 v32, 0x3f317217, v24
	v_cmp_lt_f32_e64 s[6:7], |v24|, s0
	v_add_f32_e32 v25, 1.0, v25
	v_min_f32_e32 v22, 0, v30
	v_cndmask_b32_e64 v24, v24, v32, s[6:7]
	v_cndmask_b32_e32 v32, 0, v212, vcc
	v_cmp_gt_f32_e32 vcc, s10, v29
	v_sub_f32_e32 v24, v24, v32
	v_mul_f32_e64 v30, |v30|, s70
	v_cndmask_b32_e64 v32, 0, 32, vcc
	v_ldexp_f32 v29, v29, v32
	v_log_f32_e32 v29, v29
	v_exp_f32_e32 v30, v30
	v_add_f32_e32 v26, v18, v26
	v_min_f32_e32 v18, 0, v26
	v_mul_f32_e32 v32, 0x3f317217, v29
	v_fma_f32 v32, v29, s77, -v32
	v_fmac_f32_e32 v32, 0x3377d1cf, v29
	v_fmac_f32_e32 v32, 0x3f317217, v29
	v_cmp_lt_f32_e64 s[6:7], |v29|, s0
	v_add_f32_e32 v30, 1.0, v30
	v_mul_f32_e64 v26, |v26|, s70
	v_cndmask_b32_e64 v29, v29, v32, s[6:7]
	v_cndmask_b32_e32 v32, 0, v212, vcc
	v_cmp_gt_f32_e32 vcc, s10, v25
	v_sub_f32_e32 v29, v29, v32
	v_exp_f32_e32 v26, v26
	v_cndmask_b32_e64 v32, 0, 32, vcc
	v_ldexp_f32 v25, v25, v32
	v_log_f32_e32 v25, v25
	v_add_f32_e32 v26, 1.0, v26
	v_add_f32_e32 v31, v23, v31
	v_min_f32_e32 v23, 0, v31
	v_mul_f32_e32 v32, 0x3f317217, v25
	v_fma_f32 v32, v25, s77, -v32
	v_fmac_f32_e32 v32, 0x3377d1cf, v25
	v_fmac_f32_e32 v32, 0x3f317217, v25
	v_cmp_lt_f32_e64 s[6:7], |v25|, s0
	v_mul_f32_e64 v31, |v31|, s70
	v_exp_f32_e32 v31, v31
	v_cndmask_b32_e64 v25, v25, v32, s[6:7]
	v_cndmask_b32_e32 v32, 0, v212, vcc
	v_cmp_gt_f32_e32 vcc, s10, v30
	v_sub_f32_e32 v25, v25, v32
	v_add_f32_e32 v31, 1.0, v31
	v_cndmask_b32_e64 v32, 0, 32, vcc
	v_ldexp_f32 v30, v30, v32
	v_log_f32_e32 v30, v30
	v_add_f32_e32 v27, v19, v27
	v_min_f32_e32 v19, 0, v27
	v_mul_f32_e64 v27, |v27|, s70
	v_mul_f32_e32 v32, 0x3f317217, v30
	v_fma_f32 v32, v30, s77, -v32
	v_fmac_f32_e32 v32, 0x3377d1cf, v30
	v_fmac_f32_e32 v32, 0x3f317217, v30
	v_cmp_lt_f32_e64 s[6:7], |v30|, s0
	v_exp_f32_e32 v27, v27
	v_pk_add_f32 v[20:21], v[20:21], v[28:29] neg_lo:[0,1] neg_hi:[0,1]
	v_cndmask_b32_e64 v30, v30, v32, s[6:7]
	v_cndmask_b32_e32 v32, 0, v212, vcc
	v_cmp_gt_f32_e32 vcc, s10, v26
	v_sub_f32_e32 v30, v30, v32
	v_add_f32_e32 v27, 1.0, v27
	v_cndmask_b32_e64 v32, 0, 32, vcc
	v_ldexp_f32 v26, v26, v32
	v_log_f32_e32 v26, v26
	v_pk_mul_f32 v[20:21], v[20:21], s[2:3] op_sel_hi:[1,0]
	v_pk_add_f32 v[16:17], v[16:17], v[24:25] neg_lo:[0,1] neg_hi:[0,1]
	v_lshl_add_u64 v[24:25], v[42:43], 0, v[172:173]
	v_mul_f32_e32 v32, 0x3f317217, v26
	v_fma_f32 v32, v26, s77, -v32
	v_fmac_f32_e32 v32, 0x3377d1cf, v26
	v_fmac_f32_e32 v32, 0x3f317217, v26
	v_cmp_lt_f32_e64 s[6:7], |v26|, s0
	v_pk_mul_f32 v[16:17], v[16:17], s[2:3] op_sel_hi:[1,0]
	s_nop 0
	v_cndmask_b32_e64 v26, v26, v32, s[6:7]
	v_cndmask_b32_e32 v32, 0, v212, vcc
	v_cmp_gt_f32_e32 vcc, s10, v31
	v_sub_f32_e32 v26, v26, v32
	s_nop 0
	v_cndmask_b32_e64 v32, 0, 32, vcc
	v_ldexp_f32 v31, v31, v32
	v_log_f32_e32 v31, v31
	s_nop 0
	v_mul_f32_e32 v32, 0x3f317217, v31
	v_fma_f32 v32, v31, s77, -v32
	v_fmac_f32_e32 v32, 0x3377d1cf, v31
	v_fmac_f32_e32 v32, 0x3f317217, v31
	v_cmp_lt_f32_e64 s[6:7], |v31|, s0
	s_nop 1
	v_cndmask_b32_e64 v31, v31, v32, s[6:7]
	v_cndmask_b32_e32 v32, 0, v212, vcc
	v_cmp_gt_f32_e32 vcc, s10, v27
	v_sub_f32_e32 v31, v31, v32
	v_pk_add_f32 v[22:23], v[22:23], v[30:31] neg_lo:[0,1] neg_hi:[0,1]
	v_cndmask_b32_e64 v28, 0, 32, vcc
	v_ldexp_f32 v27, v27, v28
	v_log_f32_e32 v27, v27
	v_pk_mul_f32 v[22:23], v[22:23], s[2:3] op_sel_hi:[1,0]
	v_mul_f32_e32 v28, 0x3f317217, v27
	v_fma_f32 v28, v27, s77, -v28
	v_fmac_f32_e32 v28, 0x3377d1cf, v27
	v_fmac_f32_e32 v28, 0x3f317217, v27
	v_cmp_lt_f32_e64 s[6:7], |v27|, s0
	s_nop 1
	v_cndmask_b32_e64 v27, v27, v28, s[6:7]
	v_cndmask_b32_e32 v28, 0, v212, vcc
	v_sub_f32_e32 v27, v27, v28
	v_pk_add_f32 v[18:19], v[18:19], v[26:27] neg_lo:[0,1] neg_hi:[0,1]
	s_nop 0
	v_pk_mul_f32 v[18:19], v[18:19], s[2:3] op_sel_hi:[1,0]
	global_store_dwordx4 v[24:25], v[20:23], off offset:512
	global_store_dwordx4 v[24:25], v[16:19], off offset:528

.LBB0_936:
	s_nop 1
	v_lshlrev_b64 v[16:17], 10, v[24:25]
	s_and_b64 vcc, exec, s[0:1]
	v_lshl_add_u64 v[24:25], s[8:9], 0, v[16:17]
	s_cbranch_vccz .LBB0_938
	s_lshl_b32 s0, s36, 2
	s_add_u32 s0, s67, s0
	s_addc_u32 s1, s68, 0
	v_mov_b64_e32 v[16:17], v[214:215]
	v_mov_b64_e32 v[18:19], v[216:217]
	v_mov_b64_e32 v[20:21], v[218:219]
	v_mov_b64_e32 v[22:23], v[220:221]
	s_mov_b32 s0, 0x7f800000
	s_mov_b32 s2, 0x3d800000
	v_mov_b32_e32 v173, v177
	v_add_f32_e32 v16, v8, v16
	v_add_f32_e32 v20, v12, v20
	v_min_f32_e32 v12, 0, v20
	v_mul_f32_e64 v20, |v20|, s70
	v_exp_f32_e32 v20, v20
	v_min_f32_e32 v8, 0, v16
	v_mul_f32_e64 v16, |v16|, s70
	v_exp_f32_e32 v16, v16
	v_add_f32_e32 v20, 1.0, v20
	v_cmp_gt_f32_e32 vcc, s10, v20
	v_add_f32_e32 v21, v13, v21
	v_add_f32_e32 v16, 1.0, v16
	v_cndmask_b32_e64 v31, 0, 32, vcc
	v_ldexp_f32 v20, v20, v31
	v_log_f32_e32 v20, v20
	v_min_f32_e32 v13, 0, v21
	v_mul_f32_e64 v21, |v21|, s70
	v_exp_f32_e32 v21, v21
	v_mul_f32_e32 v31, 0x3f317217, v20
	v_fma_f32 v31, v20, s77, -v31
	v_fmac_f32_e32 v31, 0x3377d1cf, v20
	v_fmac_f32_e32 v31, 0x3f317217, v20
	v_cmp_lt_f32_e64 s[4:5], |v20|, s0
	v_add_f32_e32 v21, 1.0, v21
	v_add_f32_e32 v17, v9, v17
	v_cndmask_b32_e64 v20, v20, v31, s[4:5]
	v_cndmask_b32_e32 v31, 0, v212, vcc
	v_cmp_gt_f32_e32 vcc, s10, v16
	v_sub_f32_e32 v20, v20, v31
	v_min_f32_e32 v9, 0, v17
	v_cndmask_b32_e64 v31, 0, 32, vcc
	v_ldexp_f32 v16, v16, v31
	v_log_f32_e32 v16, v16
	v_mul_f32_e64 v17, |v17|, s70
	v_exp_f32_e32 v17, v17
	v_add_f32_e32 v22, v14, v22
	v_mul_f32_e32 v31, 0x3f317217, v16
	v_fma_f32 v31, v16, s77, -v31
	v_fmac_f32_e32 v31, 0x3377d1cf, v16
	v_fmac_f32_e32 v31, 0x3f317217, v16
	v_cmp_lt_f32_e64 s[4:5], |v16|, s0
	v_add_f32_e32 v17, 1.0, v17
	v_min_f32_e32 v14, 0, v22
	v_cndmask_b32_e64 v16, v16, v31, s[4:5]
	v_cndmask_b32_e32 v31, 0, v212, vcc
	v_cmp_gt_f32_e32 vcc, s10, v21
	v_sub_f32_e32 v16, v16, v31
	v_mul_f32_e64 v22, |v22|, s70
	v_cndmask_b32_e64 v31, 0, 32, vcc
	v_ldexp_f32 v21, v21, v31
	v_log_f32_e32 v21, v21
	v_exp_f32_e32 v22, v22
	v_add_f32_e32 v18, v10, v18
	v_min_f32_e32 v10, 0, v18
	v_mul_f32_e32 v31, 0x3f317217, v21
	v_fma_f32 v31, v21, s77, -v31
	v_fmac_f32_e32 v31, 0x3377d1cf, v21
	v_fmac_f32_e32 v31, 0x3f317217, v21
	v_cmp_lt_f32_e64 s[4:5], |v21|, s0
	v_add_f32_e32 v22, 1.0, v22
	v_mul_f32_e64 v18, |v18|, s70
	v_cndmask_b32_e64 v21, v21, v31, s[4:5]
	v_cndmask_b32_e32 v31, 0, v212, vcc
	v_cmp_gt_f32_e32 vcc, s10, v17
	v_sub_f32_e32 v21, v21, v31
	v_exp_f32_e32 v18, v18
	v_cndmask_b32_e64 v31, 0, 32, vcc
	v_ldexp_f32 v17, v17, v31
	v_log_f32_e32 v17, v17
	v_add_f32_e32 v18, 1.0, v18
	v_add_f32_e32 v23, v15, v23
	v_min_f32_e32 v15, 0, v23
	v_mul_f32_e32 v31, 0x3f317217, v17
	v_fma_f32 v31, v17, s77, -v31
	v_fmac_f32_e32 v31, 0x3377d1cf, v17
	v_fmac_f32_e32 v31, 0x3f317217, v17
	v_cmp_lt_f32_e64 s[4:5], |v17|, s0
	v_mul_f32_e64 v23, |v23|, s70
	v_exp_f32_e32 v23, v23
	v_cndmask_b32_e64 v17, v17, v31, s[4:5]
	v_cndmask_b32_e32 v31, 0, v212, vcc
	v_cmp_gt_f32_e32 vcc, s10, v22
	v_sub_f32_e32 v17, v17, v31
	v_add_f32_e32 v23, 1.0, v23
	v_cndmask_b32_e64 v31, 0, 32, vcc
	v_ldexp_f32 v22, v22, v31
	v_log_f32_e32 v22, v22
	v_add_f32_e32 v19, v11, v19
	v_min_f32_e32 v11, 0, v19
	v_mul_f32_e64 v19, |v19|, s70
	v_mul_f32_e32 v31, 0x3f317217, v22
	v_fma_f32 v31, v22, s77, -v31
	v_fmac_f32_e32 v31, 0x3377d1cf, v22
	v_fmac_f32_e32 v31, 0x3f317217, v22
	v_cmp_lt_f32_e64 s[4:5], |v22|, s0
	v_exp_f32_e32 v19, v19
	v_pk_add_f32 v[12:13], v[12:13], v[20:21] neg_lo:[0,1] neg_hi:[0,1]
	v_cndmask_b32_e64 v22, v22, v31, s[4:5]
	v_cndmask_b32_e32 v31, 0, v212, vcc
	v_cmp_gt_f32_e32 vcc, s10, v18
	v_sub_f32_e32 v22, v22, v31
	v_add_f32_e32 v19, 1.0, v19
	v_cndmask_b32_e64 v31, 0, 32, vcc
	v_ldexp_f32 v18, v18, v31
	v_log_f32_e32 v18, v18
	v_pk_mul_f32 v[12:13], v[12:13], s[2:3] op_sel_hi:[1,0]
	v_pk_add_f32 v[8:9], v[8:9], v[16:17] neg_lo:[0,1] neg_hi:[0,1]
	v_lshl_add_u64 v[16:17], v[24:25], 0, v[172:173]
	v_mul_f32_e32 v31, 0x3f317217, v18
	v_fma_f32 v31, v18, s77, -v31
	v_fmac_f32_e32 v31, 0x3377d1cf, v18
	v_fmac_f32_e32 v31, 0x3f317217, v18
	v_cmp_lt_f32_e64 s[4:5], |v18|, s0
	v_pk_mul_f32 v[8:9], v[8:9], s[2:3] op_sel_hi:[1,0]
	s_nop 0
	v_cndmask_b32_e64 v18, v18, v31, s[4:5]
	v_cndmask_b32_e32 v31, 0, v212, vcc
	v_cmp_gt_f32_e32 vcc, s10, v23
	v_sub_f32_e32 v18, v18, v31
	s_nop 0
	v_cndmask_b32_e64 v31, 0, 32, vcc
	v_ldexp_f32 v23, v23, v31
	v_log_f32_e32 v23, v23
	s_nop 0
	v_mul_f32_e32 v31, 0x3f317217, v23
	v_fma_f32 v31, v23, s77, -v31
	v_fmac_f32_e32 v31, 0x3377d1cf, v23
	v_fmac_f32_e32 v31, 0x3f317217, v23
	v_cmp_lt_f32_e64 s[4:5], |v23|, s0
	s_nop 1
	v_cndmask_b32_e64 v23, v23, v31, s[4:5]
	v_cndmask_b32_e32 v31, 0, v212, vcc
	v_cmp_gt_f32_e32 vcc, s10, v19
	v_sub_f32_e32 v23, v23, v31
	v_pk_add_f32 v[14:15], v[14:15], v[22:23] neg_lo:[0,1] neg_hi:[0,1]
	v_cndmask_b32_e64 v20, 0, 32, vcc
	v_ldexp_f32 v19, v19, v20
	v_log_f32_e32 v19, v19
	v_pk_mul_f32 v[14:15], v[14:15], s[2:3] op_sel_hi:[1,0]
	v_mul_f32_e32 v20, 0x3f317217, v19
	v_fma_f32 v20, v19, s77, -v20
	v_fmac_f32_e32 v20, 0x3377d1cf, v19
	v_fmac_f32_e32 v20, 0x3f317217, v19
	v_cmp_lt_f32_e64 s[4:5], |v19|, s0
	s_nop 1
	v_cndmask_b32_e64 v19, v19, v20, s[4:5]
	v_cndmask_b32_e32 v20, 0, v212, vcc
	v_sub_f32_e32 v19, v19, v20
	v_pk_add_f32 v[10:11], v[10:11], v[18:19] neg_lo:[0,1] neg_hi:[0,1]
	s_nop 0
	v_pk_mul_f32 v[10:11], v[10:11], s[2:3] op_sel_hi:[1,0]
	global_store_dwordx4 v[16:17], v[12:15], off
	global_store_dwordx4 v[16:17], v[8:11], off offset:16

.LBB0_951:
	s_and_b64 vcc, exec, s[0:1]
	s_cbranch_vccz .LBB0_958
	s_lshl_b32 s0, s36, 2
	s_add_u32 s0, s69, s0
	s_addc_u32 s1, s88, 0
	v_mov_b64_e32 v[8:9], v[222:223]
	v_mov_b64_e32 v[10:11], v[224:225]
	v_mov_b64_e32 v[12:13], v[226:227]
	v_mov_b64_e32 v[14:15], v[228:229]
	s_mov_b32 s0, 0x7f800000
	s_mov_b32 s2, 0x3d800000
	v_mov_b32_e32 v173, v177
	v_add_f32_e32 v8, v0, v8
	v_add_f32_e32 v12, v4, v12
	v_min_f32_e32 v4, 0, v12
	v_mul_f32_e64 v12, |v12|, s70
	v_exp_f32_e32 v12, v12
	v_min_f32_e32 v0, 0, v8
	v_mul_f32_e64 v8, |v8|, s70
	v_exp_f32_e32 v8, v8
	v_add_f32_e32 v12, 1.0, v12
	v_cmp_gt_f32_e32 vcc, s10, v12
	v_add_f32_e32 v13, v5, v13
	v_add_f32_e32 v8, 1.0, v8
	v_cndmask_b32_e64 v16, 0, 32, vcc
	v_ldexp_f32 v12, v12, v16
	v_log_f32_e32 v12, v12
	v_min_f32_e32 v5, 0, v13
	v_mul_f32_e64 v13, |v13|, s70
	v_exp_f32_e32 v13, v13
	v_mul_f32_e32 v16, 0x3f317217, v12
	v_fma_f32 v16, v12, s77, -v16
	v_fmac_f32_e32 v16, 0x3377d1cf, v12
	v_fmac_f32_e32 v16, 0x3f317217, v12
	v_cmp_lt_f32_e64 s[4:5], |v12|, s0
	v_add_f32_e32 v13, 1.0, v13
	v_add_f32_e32 v9, v1, v9
	v_cndmask_b32_e64 v12, v12, v16, s[4:5]
	v_cndmask_b32_e32 v16, 0, v212, vcc
	v_cmp_gt_f32_e32 vcc, s10, v8
	v_sub_f32_e32 v12, v12, v16
	v_min_f32_e32 v1, 0, v9
	v_cndmask_b32_e64 v16, 0, 32, vcc
	v_ldexp_f32 v8, v8, v16
	v_log_f32_e32 v8, v8
	v_mul_f32_e64 v9, |v9|, s70
	v_exp_f32_e32 v9, v9
	v_add_f32_e32 v14, v6, v14
	v_mul_f32_e32 v16, 0x3f317217, v8
	v_fma_f32 v16, v8, s77, -v16
	v_fmac_f32_e32 v16, 0x3377d1cf, v8
	v_fmac_f32_e32 v16, 0x3f317217, v8
	v_cmp_lt_f32_e64 s[4:5], |v8|, s0
	v_add_f32_e32 v9, 1.0, v9
	v_min_f32_e32 v6, 0, v14
	v_cndmask_b32_e64 v8, v8, v16, s[4:5]
	v_cndmask_b32_e32 v16, 0, v212, vcc
	v_cmp_gt_f32_e32 vcc, s10, v13
	v_sub_f32_e32 v8, v8, v16
	v_mul_f32_e64 v14, |v14|, s70
	v_cndmask_b32_e64 v16, 0, 32, vcc
	v_ldexp_f32 v13, v13, v16
	v_log_f32_e32 v13, v13
	v_exp_f32_e32 v14, v14
	v_add_f32_e32 v10, v2, v10
	v_min_f32_e32 v2, 0, v10
	v_mul_f32_e32 v16, 0x3f317217, v13
	v_fma_f32 v16, v13, s77, -v16
	v_fmac_f32_e32 v16, 0x3377d1cf, v13
	v_fmac_f32_e32 v16, 0x3f317217, v13
	v_cmp_lt_f32_e64 s[4:5], |v13|, s0
	v_add_f32_e32 v14, 1.0, v14
	v_mul_f32_e64 v10, |v10|, s70
	v_cndmask_b32_e64 v13, v13, v16, s[4:5]
	v_cndmask_b32_e32 v16, 0, v212, vcc
	v_cmp_gt_f32_e32 vcc, s10, v9
	v_sub_f32_e32 v13, v13, v16
	v_exp_f32_e32 v10, v10
	v_cndmask_b32_e64 v16, 0, 32, vcc
	v_ldexp_f32 v9, v9, v16
	v_log_f32_e32 v9, v9
	v_add_f32_e32 v10, 1.0, v10
	v_add_f32_e32 v15, v7, v15
	v_min_f32_e32 v7, 0, v15
	v_mul_f32_e32 v16, 0x3f317217, v9
	v_fma_f32 v16, v9, s77, -v16
	v_fmac_f32_e32 v16, 0x3377d1cf, v9
	v_fmac_f32_e32 v16, 0x3f317217, v9
	v_cmp_lt_f32_e64 s[4:5], |v9|, s0
	v_mul_f32_e64 v15, |v15|, s70
	v_exp_f32_e32 v15, v15
	v_cndmask_b32_e64 v9, v9, v16, s[4:5]
	v_cndmask_b32_e32 v16, 0, v212, vcc
	v_cmp_gt_f32_e32 vcc, s10, v14
	v_sub_f32_e32 v9, v9, v16
	v_add_f32_e32 v15, 1.0, v15
	v_cndmask_b32_e64 v16, 0, 32, vcc
	v_ldexp_f32 v14, v14, v16
	v_log_f32_e32 v14, v14
	v_add_f32_e32 v11, v3, v11
	v_min_f32_e32 v3, 0, v11
	v_mul_f32_e64 v11, |v11|, s70
	v_mul_f32_e32 v16, 0x3f317217, v14
	v_fma_f32 v16, v14, s77, -v16
	v_fmac_f32_e32 v16, 0x3377d1cf, v14
	v_fmac_f32_e32 v16, 0x3f317217, v14
	v_cmp_lt_f32_e64 s[4:5], |v14|, s0
	v_exp_f32_e32 v11, v11
	v_pk_add_f32 v[4:5], v[4:5], v[12:13] neg_lo:[0,1] neg_hi:[0,1]
	v_cndmask_b32_e64 v14, v14, v16, s[4:5]
	v_cndmask_b32_e32 v16, 0, v212, vcc
	v_cmp_gt_f32_e32 vcc, s10, v10
	v_sub_f32_e32 v14, v14, v16
	v_add_f32_e32 v11, 1.0, v11
	v_cndmask_b32_e64 v16, 0, 32, vcc
	v_ldexp_f32 v10, v10, v16
	v_log_f32_e32 v10, v10
	v_pk_mul_f32 v[4:5], v[4:5], s[2:3] op_sel_hi:[1,0]
	v_pk_add_f32 v[0:1], v[0:1], v[8:9] neg_lo:[0,1] neg_hi:[0,1]
	v_lshl_add_u64 v[8:9], v[24:25], 0, v[172:173]
	v_mul_f32_e32 v16, 0x3f317217, v10
	v_fma_f32 v16, v10, s77, -v16
	v_fmac_f32_e32 v16, 0x3377d1cf, v10
	v_fmac_f32_e32 v16, 0x3f317217, v10
	v_cmp_lt_f32_e64 s[4:5], |v10|, s0
	v_pk_mul_f32 v[0:1], v[0:1], s[2:3] op_sel_hi:[1,0]
	s_nop 0
	v_cndmask_b32_e64 v10, v10, v16, s[4:5]
	v_cndmask_b32_e32 v16, 0, v212, vcc
	v_cmp_gt_f32_e32 vcc, s10, v15
	v_sub_f32_e32 v10, v10, v16
	s_nop 0
	v_cndmask_b32_e64 v16, 0, 32, vcc
	v_ldexp_f32 v15, v15, v16
	v_log_f32_e32 v15, v15
	s_nop 0
	v_mul_f32_e32 v16, 0x3f317217, v15
	v_fma_f32 v16, v15, s77, -v16
	v_fmac_f32_e32 v16, 0x3377d1cf, v15
	v_fmac_f32_e32 v16, 0x3f317217, v15
	v_cmp_lt_f32_e64 s[4:5], |v15|, s0
	s_nop 1
	v_cndmask_b32_e64 v15, v15, v16, s[4:5]
	v_cndmask_b32_e32 v16, 0, v212, vcc
	v_cmp_gt_f32_e32 vcc, s10, v11
	v_sub_f32_e32 v15, v15, v16
	v_pk_add_f32 v[6:7], v[6:7], v[14:15] neg_lo:[0,1] neg_hi:[0,1]
	v_cndmask_b32_e64 v12, 0, 32, vcc
	v_ldexp_f32 v11, v11, v12
	v_log_f32_e32 v11, v11
	v_pk_mul_f32 v[6:7], v[6:7], s[2:3] op_sel_hi:[1,0]
	v_mul_f32_e32 v12, 0x3f317217, v11
	v_fma_f32 v12, v11, s77, -v12
	v_fmac_f32_e32 v12, 0x3377d1cf, v11
	v_fmac_f32_e32 v12, 0x3f317217, v11
	v_cmp_lt_f32_e64 s[4:5], |v11|, s0
	s_nop 1
	v_cndmask_b32_e64 v11, v11, v12, s[4:5]
	v_cndmask_b32_e32 v12, 0, v212, vcc
	v_sub_f32_e32 v11, v11, v12
	v_pk_add_f32 v[2:3], v[2:3], v[10:11] neg_lo:[0,1] neg_hi:[0,1]
	s_nop 0
	v_pk_mul_f32 v[2:3], v[2:3], s[2:3] op_sel_hi:[1,0]
	global_store_dwordx4 v[8:9], v[4:7], off offset:512
	global_store_dwordx4 v[8:9], v[0:3], off offset:528
	s_andn2_b64 vcc, exec, s[38:39]
	s_mov_b64 s[0:1], -1
	s_cbranch_vccnz .LBB0_615
	s_branch .LBB0_959
